# nt hint on the wide loads of both norm phases (incl. the layer-0 weight transposes' f32 reads) on top of nt residual loads
# baseline (speedup 1.0000x reference)
;     __device__ __forceinline__ const float* in(int i) const { return (const float*)(const __attribute__((address_space(1))) float*)ld(i); }
;     __device__ __forceinline__ unsigned char* ws() const { return (unsigned char*)(__attribute__((address_space(1))) unsigned char*)ld(23); }
; template <bool UPMAP>
; __device__ __forceinline__ void transpose_item(const float* W, int K, int N, bf16* WT, float* scr, int item, int lane) {
;     const int nblk = N / 32, kb = item / nblk, nb = item % nblk, k0 = 64 * kb, n0 = 32 * nb;
;     { f32x4 v[8];
; #pragma unroll
;       for (int i = 0; i < 8; ++i) v[i] = *(const f32x4*)(W + (size_t)(k0 + 8 * i + (lane >> 3)) * N + n0 + 4 * (lane & 7));
; #pragma unroll
;       for (int i = 0; i < 8; ++i) { float* d = scr + (8 * i + (lane >> 3)) * 33 + 4 * (lane & 7); d[0] = v[i][0]; d[1] = v[i][1]; d[2] = v[i][2]; d[3] = v[i][3]; } }
;     LDS_WAIT();
;     const int c = lane & 7;
; #pragma unroll
;     for (int j = 0; j < 4; ++j) { const int n = (lane >> 3) + 8 * j; const float* s = scr + (8 * c) * 33 + n;
;         v4u o; o.x = pk2(s[0 * 33], s[1 * 33]); o.y = pk2(s[2 * 33], s[3 * 33]); o.z = pk2(s[4 * 33], s[5 * 33]); o.w = pk2(s[6 * 33], s[7 * 33]);
;         const int nsrc = n0 + n; int nrow = nsrc;
;         if (UPMAP) { const int bj = nsrc / 2816, chn = nsrc - bj * 2816; nrow = (chn >> 7) * 256 + bj * 128 + (chn & 127); }
;         *(v4u*)(WT + (size_t)nrow * K + k0 + 8 * c) = o; }
;     LDS_WAIT();
; }
; template <int PART>
; __device__ __forceinline__ void prologue(const KPD& kp, unsigned char* lds, int tid, int lane, int wave) {
;     ...
;     for (int it = gw; it < 2 * PER; it += NGW) {
;         const int l = it / PER; int r = it % PER;
;         if (r < I_IN) { transpose_item<false>(kp.in(I_WIN) + (size_t)l * D * INW, D, INW, (bf16*)(ws + WS_WIN) + (size_t)l * INP * D, scr, r, lane); continue; } r -= I_IN;
;         if (r < I_OUT) { transpose_item<false>(kp.in(I_WOUT) + (size_t)l * D * D, D, D, (bf16*)(ws + WS_WOUT) + (size_t)l * D * D, scr, r, lane); continue; } r -= I_OUT;
;         if (r < I_UP) { transpose_item<true>(kp.in(I_WUP) + (size_t)l * D * DFF2, D, DFF2, (bf16*)(ws + WS_WUP) + (size_t)l * DFF2 * D, scr, r, lane); continue; } r -= I_UP;
;         transpose_item<false>(kp.in(I_WDOWN) + (size_t)l * DFF * D, DFF, D, (bf16*)(ws + WS_WDN) + (size_t)l * D * DFF, scr, r, lane);
.LBB0_90:
	s_mul_hi_i32 s2, s17, 0x5ac5242b
	s_lshr_b32 s3, s2, 31
	s_ashr_i32 s2, s2, 11
	s_add_i32 s2, s2, s3
	s_mul_i32 s3, s2, 0xffffe970
	s_add_i32 s18, s17, s3
	s_cmpk_gt_i32 s18, 0x40f
	s_mov_b64 s[4:5], -1
	s_cbranch_scc0 .LBB0_100
	s_cmpk_gt_u32 s18, 0x60f
	s_cbranch_scc0 .LBB0_97
	s_cmpk_gt_u32 s18, 0x110f
	s_cbranch_scc0 .LBB0_94
	v_mov_b32_e32 v26, 0x264a8
	ds_read_b64 v[26:27], v26
	s_mul_i32 s4, s2, 0xb00000
	s_mul_hi_i32 s3, s2, 0xb00000
	s_mul_hi_i32 s5, s2, 0x580000
	v_lshlrev_b32_e32 v34, 2, v2
	s_waitcnt lgkmcnt(0)
	v_readfirstlane_b32 s20, v26
	v_readfirstlane_b32 s19, v27
	s_add_u32 s4, s20, s4
	s_addc_u32 s19, s19, s3
	s_mul_i32 s3, s2, 0x580000
	s_add_u32 s20, s6, s3
	s_addc_u32 s21, s7, s5
	s_add_i32 s3, s18, 0xeef0
	s_bfe_u32 s22, s3, 0xb0005
	s_lshl_b32 s3, s3, 5
	s_and_b32 s3, s3, 0x3e0
	s_lshl_b32 s5, s3, 2
	s_add_u32 s4, s4, s5
	s_addc_u32 s5, s19, 0
	v_lshl_add_u64 v[26:27], s[4:5], 0, v[34:35]
	v_lshl_or_b32 v34, s22, 18, v10
	v_lshl_add_u64 v[36:37], v[26:27], 0, v[34:35]
	s_mov_b32 s4, 0x8000
	v_add_co_u32_e32 v30, vcc, s4, v36
	s_mov_b32 s4, 0x10000
	s_nop 0
	v_addc_co_u32_e32 v31, vcc, 0, v37, vcc
	v_add_co_u32_e32 v42, vcc, s4, v36
	s_mov_b32 s4, 0x18000
	s_nop 0
	v_addc_co_u32_e32 v43, vcc, 0, v37, vcc
	v_add_co_u32_e32 v46, vcc, s4, v36
	s_mov_b32 s4, 0x20000
	s_nop 0
	v_addc_co_u32_e32 v47, vcc, 0, v37, vcc
	v_add_co_u32_e32 v50, vcc, s4, v36
	s_mov_b32 s4, 0x28000
	s_nop 0
	v_addc_co_u32_e32 v51, vcc, 0, v37, vcc
	v_add_co_u32_e32 v54, vcc, s4, v36
	global_load_dwordx4 v[26:29], v[36:37], off nt
	s_nop 0
	global_load_dwordx4 v[30:33], v[30:31], off nt
	v_addc_co_u32_e32 v55, vcc, 0, v37, vcc
	global_load_dwordx4 v[42:45], v[42:43], off nt
	s_nop 0
	global_load_dwordx4 v[46:49], v[46:47], off nt
	s_nop 0
	global_load_dwordx4 v[50:53], v[50:51], off nt
	s_nop 0
	global_load_dwordx4 v[54:57], v[54:55], off nt
	s_mov_b32 s4, 0x30000
	v_add_co_u32_e32 v58, vcc, s4, v36
	s_mov_b32 s4, 0x38000
	s_nop 0
	v_addc_co_u32_e32 v59, vcc, 0, v37, vcc
	global_load_dwordx4 v[58:61], v[58:59], off nt
	v_add_co_u32_e32 v36, vcc, s4, v36
	s_lshl_b32 s4, s22, 7
	s_nop 0
	v_addc_co_u32_e32 v37, vcc, 0, v37, vcc
	global_load_dwordx4 v[62:65], v[36:37], off nt
	v_or_b32_e32 v34, s3, v5
	s_add_u32 s4, s20, s4
	v_or_b32_e32 v36, s3, v6
	v_mul_u32_u24_e32 v38, 0xb00, v34
	s_addc_u32 s5, s21, 0
	v_lshlrev_b32_e32 v34, 1, v4
	v_mul_u32_u24_e32 v39, 0xb00, v36
	v_lshl_add_u64 v[36:37], s[4:5], 0, v[34:35]
	v_lshlrev_b32_e32 v34, 1, v38
	v_lshl_add_u64 v[66:67], v[36:37], 0, v[34:35]
	v_lshlrev_b32_e32 v34, 1, v39
	v_lshl_add_u64 v[68:69], v[36:37], 0, v[34:35]
	s_mov_b64 s[4:5], 0
	s_waitcnt vmcnt(7)
	ds_write2_b32 v11, v26, v27 offset1:1
	ds_write2_b32 v11, v28, v29 offset0:2 offset1:3
	s_waitcnt vmcnt(6)
	ds_write2_b32 v12, v30, v31 offset1:1
	ds_write2_b32 v13, v32, v33 offset1:1
	s_waitcnt vmcnt(5)
	ds_write2_b32 v14, v42, v43 offset1:1
	ds_write2_b32 v15, v44, v45 offset1:1
	s_waitcnt vmcnt(4)
	ds_write2_b32 v16, v46, v47 offset1:1
	ds_write2_b32 v17, v48, v49 offset1:1
	s_waitcnt vmcnt(3)
	ds_write2_b32 v18, v50, v51 offset1:1
	ds_write2_b32 v19, v52, v53 offset1:1
	s_waitcnt vmcnt(2)
	ds_write2_b32 v20, v54, v55 offset1:1
	ds_write2_b32 v21, v56, v57 offset1:1
	s_waitcnt vmcnt(1)
	ds_write2_b32 v22, v58, v59 offset1:1
	ds_write2_b32 v23, v60, v61 offset1:1
	s_waitcnt vmcnt(0)
	ds_write2_b32 v24, v62, v63 offset1:1
	ds_write2_b32 v25, v64, v65 offset1:1
	s_waitcnt lgkmcnt(0)
	ds_read2_b32 v[30:31], v9 offset0:33 offset1:41
	ds_read2_b32 v[32:33], v9 offset1:8
	ds_read2_b32 v[42:43], v9 offset0:66 offset1:74
	ds_read2_b32 v[44:45], v9 offset0:99 offset1:107
	ds_read2_b32 v[46:47], v9 offset0:132 offset1:140
	ds_read2_b32 v[48:49], v9 offset0:165 offset1:173
	ds_read2_b32 v[50:51], v9 offset0:198 offset1:206
	ds_read2_b32 v[52:53], v9 offset0:231 offset1:239
	ds_read2_b32 v[54:55], v9 offset0:16 offset1:24
	ds_read2_b32 v[56:57], v9 offset0:49 offset1:57
	s_waitcnt lgkmcnt(8)
	v_cvt_pk_bf16_f32 v26, v32, v30
	s_waitcnt lgkmcnt(6)
	v_cvt_pk_bf16_f32 v27, v42, v44
	s_waitcnt lgkmcnt(4)
	v_cvt_pk_bf16_f32 v28, v46, v48
	s_waitcnt lgkmcnt(2)
	v_cvt_pk_bf16_f32 v29, v50, v52
	global_store_dwordx4 v[66:67], v[26:29], off
	v_cvt_pk_bf16_f32 v30, v33, v31
	v_cvt_pk_bf16_f32 v31, v43, v45
	v_cvt_pk_bf16_f32 v32, v47, v49
	v_cvt_pk_bf16_f32 v33, v51, v53
	ds_read2_b32 v[42:43], v9 offset0:82 offset1:90
	ds_read2_b32 v[44:45], v9 offset0:115 offset1:123
	ds_read2_b32 v[46:47], v9 offset0:148 offset1:156
	ds_read2_b32 v[48:49], v9 offset0:181 offset1:189
	ds_read2_b32 v[50:51], v9 offset0:214 offset1:222
	ds_read2_b32 v[52:53], v9 offset0:247 offset1:255
	global_store_dwordx4 v[68:69], v[30:33], off
	s_waitcnt lgkmcnt(6)
	v_cvt_pk_bf16_f32 v26, v54, v56
	s_waitcnt lgkmcnt(4)
	v_cvt_pk_bf16_f32 v27, v42, v44
	s_waitcnt lgkmcnt(2)
	v_cvt_pk_bf16_f32 v28, v46, v48
	s_waitcnt lgkmcnt(0)
	v_cvt_pk_bf16_f32 v29, v50, v52
	v_or_b32_e32 v30, s3, v7
	v_mul_u32_u24_e32 v30, 0xb00, v30
	v_lshlrev_b32_e32 v34, 1, v30
	v_lshl_add_u64 v[30:31], v[36:37], 0, v[34:35]
	global_store_dwordx4 v[30:31], v[26:29], off
	v_or_b32_e32 v30, s3, v8
	v_mul_u32_u24_e32 v30, 0xb00, v30
	v_lshlrev_b32_e32 v34, 1, v30
	v_lshl_add_u64 v[30:31], v[36:37], 0, v[34:35]
	v_cvt_pk_bf16_f32 v26, v55, v57
	v_cvt_pk_bf16_f32 v27, v43, v45
	v_cvt_pk_bf16_f32 v28, v47, v49
	v_cvt_pk_bf16_f32 v29, v51, v53
	global_store_dwordx4 v[30:31], v[26:29], off
	s_waitcnt lgkmcnt(0)
; __device__ __forceinline__ unsigned pk2(float lo, float hi) { return cvtpk(lo, hi); }
; #define LDS_WAIT() asm volatile("s_waitcnt lgkmcnt(0)" ::: "memory")
; template <bool UPMAP>
; __device__ __forceinline__ void transpose_item(const float* W, int K, int N, bf16* WT, float* scr, int item, int lane) {
;     const int nblk = N / 32, kb = item / nblk, nb = item % nblk, k0 = 64 * kb, n0 = 32 * nb;
;     { f32x4 v[8];
; #pragma unroll
;       for (int i = 0; i < 8; ++i) v[i] = *(const f32x4*)(W + (size_t)(k0 + 8 * i + (lane >> 3)) * N + n0 + 4 * (lane & 7));
; #pragma unroll
;       for (int i = 0; i < 8; ++i) { float* d = scr + (8 * i + (lane >> 3)) * 33 + 4 * (lane & 7); d[0] = v[i][0]; d[1] = v[i][1]; d[2] = v[i][2]; d[3] = v[i][3]; } }
;     LDS_WAIT();
;     const int c = lane & 7;
; #pragma unroll
;     for (int j = 0; j < 4; ++j) { const int n = (lane >> 3) + 8 * j; const float* s = scr + (8 * c) * 33 + n;
;         v4u o; o.x = pk2(s[0 * 33], s[1 * 33]); o.y = pk2(s[2 * 33], s[3 * 33]); o.z = pk2(s[4 * 33], s[5 * 33]); o.w = pk2(s[6 * 33], s[7 * 33]);
;         const int nsrc = n0 + n; int nrow = nsrc;
;         if (UPMAP) { const int bj = nsrc / 2816, chn = nsrc - bj * 2816; nrow = (chn >> 7) * 256 + bj * 128 + (chn & 127); }
;         *(v4u*)(WT + (size_t)nrow * K + k0 + 8 * c) = o; }
;     LDS_WAIT();
; }
.LBB0_94:
	s_andn2_b64 vcc, exec, s[4:5]
	s_cbranch_vccnz .LBB0_96
	v_mov_b32_e32 v26, 0x26490
	ds_read_b64 v[26:27], v26
	s_mul_i32 s4, s2, 0x1600000
	s_mul_hi_i32 s3, s2, 0x1600000
	s_mul_hi_i32 s5, s2, 0xb00000
	v_lshlrev_b32_e32 v34, 2, v2
	s_waitcnt lgkmcnt(0)
	v_readfirstlane_b32 s20, v26
	v_readfirstlane_b32 s19, v27
	s_add_u32 s4, s20, s4
	s_addc_u32 s3, s19, s3
	s_mul_i32 s19, s2, 0xb00000
	s_add_u32 s19, s9, s19
	s_addc_u32 s20, s10, s5
	s_add_i32 s5, s18, 0xf9f0
	s_and_b32 s21, s5, 0xffff
	s_mul_i32 s21, s21, 0xba2f
	s_lshr_b32 s21, s21, 23
	s_mul_i32 s22, s21, 0xb0
	s_sub_i32 s22, s5, s22
	s_lshl_b32 s23, s22, 5
	s_and_b32 s24, s23, 0xffe0
	s_lshl_b32 s5, s24, 2
	v_lshl_or_b32 v28, s21, 6, v5
	s_add_u32 s4, s4, s5
	s_addc_u32 s5, s3, 0
	v_mul_u32_u24_e32 v28, 0x1600, v28
	v_lshl_add_u64 v[26:27], s[4:5], 0, v[34:35]
	v_lshlrev_b32_e32 v34, 2, v28
	v_lshl_add_u64 v[36:37], v[26:27], 0, v[34:35]
	s_mov_b32 s3, 0x2c000
	v_add_co_u32_e32 v30, vcc, s3, v36
	s_mov_b32 s3, 0x58000
	s_nop 0
	v_addc_co_u32_e32 v31, vcc, 0, v37, vcc
	v_add_co_u32_e32 v42, vcc, s3, v36
	s_mov_b32 s3, 0x84000
	s_nop 0
	v_addc_co_u32_e32 v43, vcc, 0, v37, vcc
	v_add_co_u32_e32 v46, vcc, s3, v36
	s_mov_b32 s3, 0xb0000
	s_nop 0
	v_addc_co_u32_e32 v47, vcc, 0, v37, vcc
	v_add_co_u32_e32 v50, vcc, s3, v36
	s_mov_b32 s3, 0xdc000
	s_nop 0
	v_addc_co_u32_e32 v51, vcc, 0, v37, vcc
	v_add_co_u32_e32 v54, vcc, s3, v36
	global_load_dwordx4 v[26:29], v[36:37], off nt
	s_nop 0
	global_load_dwordx4 v[30:33], v[30:31], off nt
	v_addc_co_u32_e32 v55, vcc, 0, v37, vcc
	global_load_dwordx4 v[42:45], v[42:43], off nt
	s_nop 0
	global_load_dwordx4 v[46:49], v[46:47], off nt
	s_nop 0
	global_load_dwordx4 v[50:53], v[50:51], off nt
	s_nop 0
	global_load_dwordx4 v[54:57], v[54:55], off nt
	s_mov_b32 s3, 0x108000
	v_add_co_u32_e32 v58, vcc, s3, v36
	s_mov_b32 s3, 0x134000
	s_nop 0
	v_addc_co_u32_e32 v59, vcc, 0, v37, vcc
	global_load_dwordx4 v[58:61], v[58:59], off nt
	v_add_co_u32_e32 v36, vcc, s3, v36
	s_and_b32 s3, s22, 0xffff
	s_nop 0
	v_addc_co_u32_e32 v37, vcc, 0, v37, vcc
	global_load_dwordx4 v[62:65], v[36:37], off nt
	s_cmpk_gt_u32 s3, 0x57
	s_cselect_b32 s3, 0xfffff500, 0
	s_cselect_b32 s22, 0x80, 0
	s_lshl_b32 s4, s21, 7
	s_add_u32 s4, s19, s4
	s_addc_u32 s5, s20, 0
	s_add_i32 s3, s3, s24
	v_lshlrev_b32_e32 v34, 1, v4
	s_and_b32 s19, s23, 0x60
	s_lshl_b32 s3, s3, 1
	v_lshl_add_u64 v[36:37], s[4:5], 0, v[34:35]
	s_or_b32 s4, s19, s22
	s_and_b32 s3, s3, 0xffffff00
	s_or_b32 s3, s4, s3
	v_or_b32_e32 v66, s3, v5
	v_ashrrev_i32_e32 v67, 31, v66
	s_waitcnt vmcnt(7)
	ds_write2_b32 v11, v26, v27 offset1:1
	ds_write2_b32 v11, v28, v29 offset0:2 offset1:3
	s_waitcnt vmcnt(6)
	ds_write2_b32 v12, v30, v31 offset1:1
	ds_write2_b32 v13, v32, v33 offset1:1
	s_waitcnt vmcnt(5)
	ds_write2_b32 v14, v42, v43 offset1:1
	ds_write2_b32 v15, v44, v45 offset1:1
	s_waitcnt vmcnt(4)
	ds_write2_b32 v16, v46, v47 offset1:1
	ds_write2_b32 v17, v48, v49 offset1:1
	s_waitcnt vmcnt(3)
	ds_write2_b32 v18, v50, v51 offset1:1
	ds_write2_b32 v19, v52, v53 offset1:1
	s_waitcnt vmcnt(2)
	ds_write2_b32 v20, v54, v55 offset1:1
	ds_write2_b32 v21, v56, v57 offset1:1
	s_waitcnt vmcnt(1)
	ds_write2_b32 v22, v58, v59 offset1:1
	ds_write2_b32 v23, v60, v61 offset1:1
	s_waitcnt vmcnt(0)
	ds_write2_b32 v24, v62, v63 offset1:1
	ds_write2_b32 v25, v64, v65 offset1:1
	s_waitcnt lgkmcnt(0)
	ds_read2_b32 v[30:31], v9 offset0:33 offset1:41
	ds_read2_b32 v[32:33], v9 offset1:8
	ds_read2_b32 v[42:43], v9 offset0:66 offset1:74
	ds_read2_b32 v[44:45], v9 offset0:99 offset1:107
	ds_read2_b32 v[46:47], v9 offset0:132 offset1:140
	ds_read2_b32 v[48:49], v9 offset0:165 offset1:173
	ds_read2_b32 v[50:51], v9 offset0:198 offset1:206
	ds_read2_b32 v[52:53], v9 offset0:231 offset1:239
	v_lshlrev_b64 v[54:55], 11, v[66:67]
	s_waitcnt lgkmcnt(6)
	v_cvt_pk_bf16_f32 v26, v32, v30
	v_lshl_add_u64 v[54:55], v[36:37], 0, v[54:55]
	v_or_b32_e32 v30, s3, v6
	s_waitcnt lgkmcnt(4)
	v_cvt_pk_bf16_f32 v27, v42, v44
	s_waitcnt lgkmcnt(2)
	v_cvt_pk_bf16_f32 v28, v46, v48
	s_waitcnt lgkmcnt(0)
	v_cvt_pk_bf16_f32 v29, v50, v52
	global_store_dwordx4 v[54:55], v[26:29], off
	s_nop 1
	v_cvt_pk_bf16_f32 v26, v33, v31
	v_ashrrev_i32_e32 v31, 31, v30
	v_lshlrev_b64 v[30:31], 11, v[30:31]
	v_cvt_pk_bf16_f32 v27, v43, v45
	v_cvt_pk_bf16_f32 v28, v47, v49
	v_cvt_pk_bf16_f32 v29, v51, v53
	v_lshl_add_u64 v[30:31], v[36:37], 0, v[30:31]
	ds_read2_b32 v[32:33], v9 offset0:16 offset1:24
	ds_read2_b32 v[42:43], v9 offset0:49 offset1:57
	ds_read2_b32 v[44:45], v9 offset0:82 offset1:90
	ds_read2_b32 v[46:47], v9 offset0:115 offset1:123
	ds_read2_b32 v[48:49], v9 offset0:148 offset1:156
	ds_read2_b32 v[50:51], v9 offset0:181 offset1:189
	ds_read2_b32 v[52:53], v9 offset0:214 offset1:222
	ds_read2_b32 v[54:55], v9 offset0:247 offset1:255
	global_store_dwordx4 v[30:31], v[26:29], off
	v_or_b32_e32 v30, s3, v7
	v_ashrrev_i32_e32 v31, 31, v30
	v_lshlrev_b64 v[30:31], 11, v[30:31]
	v_lshl_add_u64 v[30:31], v[36:37], 0, v[30:31]
	s_waitcnt lgkmcnt(6)
	v_cvt_pk_bf16_f32 v26, v32, v42
	s_waitcnt lgkmcnt(4)
	v_cvt_pk_bf16_f32 v27, v44, v46
	s_waitcnt lgkmcnt(2)
	v_cvt_pk_bf16_f32 v28, v48, v50
	s_waitcnt lgkmcnt(0)
	v_cvt_pk_bf16_f32 v29, v52, v54
	global_store_dwordx4 v[30:31], v[26:29], off
	v_or_b32_e32 v30, s3, v8
	v_ashrrev_i32_e32 v31, 31, v30
	v_lshlrev_b64 v[30:31], 11, v[30:31]
	v_lshl_add_u64 v[30:31], v[36:37], 0, v[30:31]
	v_cvt_pk_bf16_f32 v26, v33, v43
	v_cvt_pk_bf16_f32 v27, v45, v47
	v_cvt_pk_bf16_f32 v28, v49, v51
	v_cvt_pk_bf16_f32 v29, v53, v55
	global_store_dwordx4 v[30:31], v[26:29], off
	s_waitcnt lgkmcnt(0)

;     __device__ __forceinline__ const float* in(int i) const { return (const float*)(const __attribute__((address_space(1))) float*)ld(i); }
;     __device__ __forceinline__ unsigned char* ws() const { return (unsigned char*)(__attribute__((address_space(1))) unsigned char*)ld(23); }
; __device__ __forceinline__ unsigned pk2(float lo, float hi) { return cvtpk(lo, hi); }
; #define LDS_WAIT() asm volatile("s_waitcnt lgkmcnt(0)" ::: "memory")
; template <bool UPMAP>
; __device__ __forceinline__ void transpose_item(const float* W, int K, int N, bf16* WT, float* scr, int item, int lane) {
;     const int nblk = N / 32, kb = item / nblk, nb = item % nblk, k0 = 64 * kb, n0 = 32 * nb;
;     { f32x4 v[8];
; #pragma unroll
;       for (int i = 0; i < 8; ++i) v[i] = *(const f32x4*)(W + (size_t)(k0 + 8 * i + (lane >> 3)) * N + n0 + 4 * (lane & 7));
; #pragma unroll
;       for (int i = 0; i < 8; ++i) { float* d = scr + (8 * i + (lane >> 3)) * 33 + 4 * (lane & 7); d[0] = v[i][0]; d[1] = v[i][1]; d[2] = v[i][2]; d[3] = v[i][3]; } }
;     LDS_WAIT();
;     const int c = lane & 7;
; #pragma unroll
;     for (int j = 0; j < 4; ++j) { const int n = (lane >> 3) + 8 * j; const float* s = scr + (8 * c) * 33 + n;
;         v4u o; o.x = pk2(s[0 * 33], s[1 * 33]); o.y = pk2(s[2 * 33], s[3 * 33]); o.z = pk2(s[4 * 33], s[5 * 33]); o.w = pk2(s[6 * 33], s[7 * 33]);
;         const int nsrc = n0 + n; int nrow = nsrc;
;         if (UPMAP) { const int bj = nsrc / 2816, chn = nsrc - bj * 2816; nrow = (chn >> 7) * 256 + bj * 128 + (chn & 127); }
;         *(v4u*)(WT + (size_t)nrow * K + k0 + 8 * c) = o; }
;     LDS_WAIT();
; template <int PART>
; __device__ __forceinline__ void prologue(const KPD& kp, unsigned char* lds, int tid, int lane, int wave) {
;     ...
;         if (r < I_OUT) { transpose_item<false>(kp.in(I_WOUT) + (size_t)l * D * D, D, D, (bf16*)(ws + WS_WOUT) + (size_t)l * D * D, scr, r, lane); continue; } r -= I_OUT;
.LBB0_97:
	s_andn2_b64 vcc, exec, s[4:5]
	s_cbranch_vccnz .LBB0_99
	v_mov_b32_e32 v26, 0x26480
	ds_read_b64 v[26:27], v26
	s_ashr_i32 s3, s2, 31
	s_lshl_b64 s[4:5], s[2:3], 22
	v_lshlrev_b32_e32 v34, 2, v2
	s_waitcnt lgkmcnt(0)
	v_readfirstlane_b32 s20, v26
	v_readfirstlane_b32 s19, v27
	s_add_u32 s20, s20, s4
	s_addc_u32 s19, s19, s5
	s_lshl_b64 s[4:5], s[2:3], 21
	s_add_u32 s21, s11, s4
	s_addc_u32 s22, s12, s5
	s_add_i32 s3, s18, 0xfbf0
	s_bfe_u32 s23, s3, 0xb0005
	s_lshl_b32 s3, s3, 5
	s_and_b32 s3, s3, 0x3e0
	s_lshl_b32 s4, s3, 2
	s_add_u32 s4, s20, s4
	s_addc_u32 s5, s19, 0
	v_lshl_add_u64 v[26:27], s[4:5], 0, v[34:35]
	v_lshl_or_b32 v34, s23, 18, v10
	v_lshl_add_u64 v[36:37], v[26:27], 0, v[34:35]
	s_mov_b32 s4, 0x8000
	v_add_co_u32_e32 v30, vcc, s4, v36
	s_mov_b32 s4, 0x10000
	s_nop 0
	v_addc_co_u32_e32 v31, vcc, 0, v37, vcc
	v_add_co_u32_e32 v42, vcc, s4, v36
	s_mov_b32 s4, 0x18000
	s_nop 0
	v_addc_co_u32_e32 v43, vcc, 0, v37, vcc
	v_add_co_u32_e32 v46, vcc, s4, v36
	s_mov_b32 s4, 0x20000
	s_nop 0
	v_addc_co_u32_e32 v47, vcc, 0, v37, vcc
	v_add_co_u32_e32 v50, vcc, s4, v36
	s_mov_b32 s4, 0x28000
	s_nop 0
	v_addc_co_u32_e32 v51, vcc, 0, v37, vcc
	v_add_co_u32_e32 v54, vcc, s4, v36
	global_load_dwordx4 v[26:29], v[36:37], off nt
	s_nop 0
	global_load_dwordx4 v[30:33], v[30:31], off nt
	v_addc_co_u32_e32 v55, vcc, 0, v37, vcc
	global_load_dwordx4 v[42:45], v[42:43], off nt
	s_nop 0
	global_load_dwordx4 v[46:49], v[46:47], off nt
	s_nop 0
	global_load_dwordx4 v[50:53], v[50:51], off nt
	s_nop 0
	global_load_dwordx4 v[54:57], v[54:55], off nt
	s_mov_b32 s4, 0x30000
	v_add_co_u32_e32 v58, vcc, s4, v36
	s_mov_b32 s4, 0x38000
	s_nop 0
	v_addc_co_u32_e32 v59, vcc, 0, v37, vcc
	global_load_dwordx4 v[58:61], v[58:59], off nt
	v_add_co_u32_e32 v36, vcc, s4, v36
	s_lshl_b32 s4, s23, 7
	s_nop 0
	v_addc_co_u32_e32 v37, vcc, 0, v37, vcc
	global_load_dwordx4 v[62:65], v[36:37], off nt
	s_add_u32 s4, s21, s4
	v_or_b32_e32 v38, s3, v5
	s_addc_u32 s5, s22, 0
	v_lshlrev_b32_e32 v34, 1, v4
	v_lshl_add_u64 v[36:37], s[4:5], 0, v[34:35]
	v_lshlrev_b32_e32 v34, 11, v38
	v_lshl_add_u64 v[66:67], v[36:37], 0, v[34:35]
	v_or_b32_e32 v39, s3, v6
	v_lshlrev_b32_e32 v34, 11, v39
	v_lshl_add_u64 v[68:69], v[36:37], 0, v[34:35]
	s_waitcnt vmcnt(7)
	ds_write2_b32 v11, v26, v27 offset1:1
	ds_write2_b32 v11, v28, v29 offset0:2 offset1:3
	s_waitcnt vmcnt(6)
	ds_write2_b32 v12, v30, v31 offset1:1
	ds_write2_b32 v13, v32, v33 offset1:1
	s_waitcnt vmcnt(5)
	ds_write2_b32 v14, v42, v43 offset1:1
	ds_write2_b32 v15, v44, v45 offset1:1
	s_waitcnt vmcnt(4)
	ds_write2_b32 v16, v46, v47 offset1:1
	ds_write2_b32 v17, v48, v49 offset1:1
	s_waitcnt vmcnt(3)
	ds_write2_b32 v18, v50, v51 offset1:1
	ds_write2_b32 v19, v52, v53 offset1:1
	s_waitcnt vmcnt(2)
	ds_write2_b32 v20, v54, v55 offset1:1
	ds_write2_b32 v21, v56, v57 offset1:1
	s_waitcnt vmcnt(1)
	ds_write2_b32 v22, v58, v59 offset1:1
	ds_write2_b32 v23, v60, v61 offset1:1
	s_waitcnt vmcnt(0)
	ds_write2_b32 v24, v62, v63 offset1:1
	ds_write2_b32 v25, v64, v65 offset1:1
	s_waitcnt lgkmcnt(0)
	ds_read2_b32 v[30:31], v9 offset0:33 offset1:41
	ds_read2_b32 v[32:33], v9 offset1:8
	ds_read2_b32 v[42:43], v9 offset0:66 offset1:74
	ds_read2_b32 v[44:45], v9 offset0:99 offset1:107
	ds_read2_b32 v[46:47], v9 offset0:132 offset1:140
	ds_read2_b32 v[48:49], v9 offset0:165 offset1:173
	ds_read2_b32 v[50:51], v9 offset0:198 offset1:206
	ds_read2_b32 v[52:53], v9 offset0:231 offset1:239
	ds_read2_b32 v[54:55], v9 offset0:16 offset1:24
	ds_read2_b32 v[56:57], v9 offset0:49 offset1:57
	ds_read2_b32 v[58:59], v9 offset0:82 offset1:90
	ds_read2_b32 v[60:61], v9 offset0:115 offset1:123
	ds_read2_b32 v[62:63], v9 offset0:148 offset1:156
	s_waitcnt lgkmcnt(11)
	v_cvt_pk_bf16_f32 v26, v32, v30
	s_waitcnt lgkmcnt(9)
	v_cvt_pk_bf16_f32 v27, v42, v44
	s_waitcnt lgkmcnt(7)
	v_cvt_pk_bf16_f32 v28, v46, v48
	s_waitcnt lgkmcnt(5)
	v_cvt_pk_bf16_f32 v29, v50, v52
	global_store_dwordx4 v[66:67], v[26:29], off
	v_cvt_pk_bf16_f32 v30, v33, v31
	v_cvt_pk_bf16_f32 v31, v43, v45
	v_cvt_pk_bf16_f32 v32, v47, v49
	ds_read2_b32 v[42:43], v9 offset0:181 offset1:189
	ds_read2_b32 v[44:45], v9 offset0:214 offset1:222
	ds_read2_b32 v[46:47], v9 offset0:247 offset1:255
	v_cvt_pk_bf16_f32 v33, v51, v53
	global_store_dwordx4 v[68:69], v[30:33], off
	s_waitcnt lgkmcnt(6)
	v_cvt_pk_bf16_f32 v26, v54, v56
	s_waitcnt lgkmcnt(4)
	v_cvt_pk_bf16_f32 v27, v58, v60
	s_waitcnt lgkmcnt(2)
	v_cvt_pk_bf16_f32 v28, v62, v42
	s_waitcnt lgkmcnt(0)
	v_cvt_pk_bf16_f32 v29, v44, v46
	v_or_b32_e32 v30, s3, v7
	v_lshlrev_b32_e32 v34, 11, v30
	v_lshl_add_u64 v[30:31], v[36:37], 0, v[34:35]
	global_store_dwordx4 v[30:31], v[26:29], off
	v_or_b32_e32 v30, s3, v8
	v_lshlrev_b32_e32 v34, 11, v30
	v_lshl_add_u64 v[30:31], v[36:37], 0, v[34:35]
	v_cvt_pk_bf16_f32 v26, v55, v57
	v_cvt_pk_bf16_f32 v27, v59, v61
	v_cvt_pk_bf16_f32 v28, v63, v43
	v_cvt_pk_bf16_f32 v29, v45, v47
	global_store_dwordx4 v[30:31], v[26:29], off
	s_waitcnt lgkmcnt(0)

;     __device__ __forceinline__ const float* in(int i) const { return (const float*)(const __attribute__((address_space(1))) float*)ld(i); }
;     __device__ __forceinline__ unsigned char* ws() const { return (unsigned char*)(__attribute__((address_space(1))) unsigned char*)ld(23); }
; __device__ __forceinline__ unsigned pk2(float lo, float hi) { return cvtpk(lo, hi); }
; #define LDS_WAIT() asm volatile("s_waitcnt lgkmcnt(0)" ::: "memory")
; template <bool UPMAP>
; __device__ __forceinline__ void transpose_item(const float* W, int K, int N, bf16* WT, float* scr, int item, int lane) {
;     const int nblk = N / 32, kb = item / nblk, nb = item % nblk, k0 = 64 * kb, n0 = 32 * nb;
;     { f32x4 v[8];
; #pragma unroll
;       for (int i = 0; i < 8; ++i) v[i] = *(const f32x4*)(W + (size_t)(k0 + 8 * i + (lane >> 3)) * N + n0 + 4 * (lane & 7));
; #pragma unroll
;       for (int i = 0; i < 8; ++i) { float* d = scr + (8 * i + (lane >> 3)) * 33 + 4 * (lane & 7); d[0] = v[i][0]; d[1] = v[i][1]; d[2] = v[i][2]; d[3] = v[i][3]; } }
;     LDS_WAIT();
;     const int c = lane & 7;
; #pragma unroll
;     for (int j = 0; j < 4; ++j) { const int n = (lane >> 3) + 8 * j; const float* s = scr + (8 * c) * 33 + n;
;         v4u o; o.x = pk2(s[0 * 33], s[1 * 33]); o.y = pk2(s[2 * 33], s[3 * 33]); o.z = pk2(s[4 * 33], s[5 * 33]); o.w = pk2(s[6 * 33], s[7 * 33]);
;         const int nsrc = n0 + n; int nrow = nsrc;
;         if (UPMAP) { const int bj = nsrc / 2816, chn = nsrc - bj * 2816; nrow = (chn >> 7) * 256 + bj * 128 + (chn & 127); }
;         *(v4u*)(WT + (size_t)nrow * K + k0 + 8 * c) = o; }
;     LDS_WAIT();
; template <int PART>
; __device__ __forceinline__ void prologue(const KPD& kp, unsigned char* lds, int tid, int lane, int wave) {
;     ...
;         if (r < I_IN) { transpose_item<false>(kp.in(I_WIN) + (size_t)l * D * INW, D, INW, (bf16*)(ws + WS_WIN) + (size_t)l * INP * D, scr, r, lane); continue; } r -= I_IN;
.LBB0_101:
	v_mov_b32_e32 v26, 0x26438
	ds_read_b64 v[26:27], v26
	s_mul_i32 s4, s2, 0x820000
	s_mul_hi_i32 s3, s2, 0x820000
	s_mul_hi_i32 s5, s2, 0x480000
	s_mul_i32 s2, s2, 0x480000
	s_waitcnt lgkmcnt(0)
	v_readfirstlane_b32 s20, v26
	v_readfirstlane_b32 s19, v27
	s_add_u32 s20, s20, s4
	s_addc_u32 s21, s19, s3
	s_add_u32 s22, s13, s2
	s_mul_i32 s2, s18, 0xfc1
	s_addc_u32 s23, s16, s5
	s_lshr_b32 s3, s2, 31
	s_ashr_i32 s2, s2, 18
	s_add_i32 s2, s2, s3
	s_mul_i32 s3, s2, 0x41
	s_sub_i32 s3, s18, s3
	s_sext_i32_i16 s3, s3
	s_lshl_b32 s4, s2, 6
	s_lshl_b32 s2, s3, 5
	s_ashr_i32 s3, s2, 31
	s_lshl_b64 s[18:19], s[2:3], 2
	v_or_b32_e32 v28, s4, v5
	s_add_u32 s18, s20, s18
	s_addc_u32 s19, s21, s19
	v_lshlrev_b32_e32 v34, 2, v2
	v_mul_i32_i24_e32 v28, 0x820, v28
	v_lshl_add_u64 v[26:27], s[18:19], 0, v[34:35]
	v_ashrrev_i32_e32 v29, 31, v28
	v_lshl_add_u64 v[36:37], v[28:29], 2, v[26:27]
	s_mov_b32 s3, 0x10000
	v_add_co_u32_e32 v30, vcc, s3, v36
	s_mov_b32 s3, 0x20000
	s_nop 0
	v_addc_co_u32_e32 v31, vcc, 0, v37, vcc
	v_add_co_u32_e32 v42, vcc, s3, v36
	s_mov_b32 s3, 0x30000
	s_nop 0
	v_addc_co_u32_e32 v43, vcc, 0, v37, vcc
	v_add_co_u32_e32 v46, vcc, s3, v36
	s_mov_b32 s3, 0x41000
	s_nop 0
	v_addc_co_u32_e32 v47, vcc, 0, v37, vcc
	v_add_co_u32_e32 v50, vcc, s3, v36
	s_mov_b32 s3, 0x51000
	s_nop 0
	v_addc_co_u32_e32 v51, vcc, 0, v37, vcc
	v_add_co_u32_e32 v54, vcc, s3, v36
	global_load_dwordx4 v[26:29], v[36:37], off nt
	s_nop 0
	global_load_dwordx4 v[30:33], v[30:31], off offset:1024 nt
	v_addc_co_u32_e32 v55, vcc, 0, v37, vcc
	global_load_dwordx4 v[42:45], v[42:43], off offset:2048 nt
	s_nop 0
	global_load_dwordx4 v[46:49], v[46:47], off offset:3072 nt
	s_nop 0
	global_load_dwordx4 v[50:53], v[50:51], off nt
	s_nop 0
	global_load_dwordx4 v[54:57], v[54:55], off offset:1024 nt
	s_mov_b32 s3, 0x61000
	v_add_co_u32_e32 v58, vcc, s3, v36
	s_mov_b32 s3, 0x71000
	s_nop 0
	v_addc_co_u32_e32 v59, vcc, 0, v37, vcc
	global_load_dwordx4 v[58:61], v[58:59], off offset:2048 nt
	v_add_co_u32_e32 v36, vcc, s3, v36
	s_ashr_i32 s5, s4, 31
	s_nop 0
	v_addc_co_u32_e32 v37, vcc, 0, v37, vcc
	global_load_dwordx4 v[62:65], v[36:37], off offset:3072 nt
	s_lshl_b64 s[4:5], s[4:5], 1
	v_or_b32_e32 v36, s2, v5
	s_add_u32 s4, s22, s4
	v_ashrrev_i32_e32 v37, 31, v36
	v_lshlrev_b32_e32 v34, 1, v4
	s_addc_u32 s5, s23, s5
	v_or_b32_e32 v66, s2, v6
	v_lshlrev_b64 v[36:37], 11, v[36:37]
	v_lshl_add_u64 v[68:69], s[4:5], 0, v[34:35]
	v_lshl_add_u64 v[36:37], v[68:69], 0, v[36:37]
	v_ashrrev_i32_e32 v67, 31, v66
	s_waitcnt vmcnt(7)
	ds_write2_b32 v11, v26, v27 offset1:1
	ds_write2_b32 v11, v28, v29 offset0:2 offset1:3
	s_waitcnt vmcnt(6)
	ds_write2_b32 v12, v30, v31 offset1:1
	ds_write2_b32 v13, v32, v33 offset1:1
	s_waitcnt vmcnt(5)
	ds_write2_b32 v14, v42, v43 offset1:1
	ds_write2_b32 v15, v44, v45 offset1:1
	s_waitcnt vmcnt(4)
	ds_write2_b32 v16, v46, v47 offset1:1
	ds_write2_b32 v17, v48, v49 offset1:1
	s_waitcnt vmcnt(3)
	ds_write2_b32 v18, v50, v51 offset1:1
	ds_write2_b32 v19, v52, v53 offset1:1
	s_waitcnt vmcnt(2)
	ds_write2_b32 v20, v54, v55 offset1:1
	ds_write2_b32 v21, v56, v57 offset1:1
	s_waitcnt vmcnt(1)
	ds_write2_b32 v22, v58, v59 offset1:1
	ds_write2_b32 v23, v60, v61 offset1:1
	s_waitcnt vmcnt(0)
	ds_write2_b32 v24, v62, v63 offset1:1
	ds_write2_b32 v25, v64, v65 offset1:1
	s_waitcnt lgkmcnt(0)
	ds_read2_b32 v[30:31], v9 offset0:33 offset1:41
	ds_read2_b32 v[32:33], v9 offset1:8
	ds_read2_b32 v[42:43], v9 offset0:66 offset1:74
	ds_read2_b32 v[44:45], v9 offset0:99 offset1:107
	ds_read2_b32 v[46:47], v9 offset0:132 offset1:140
	ds_read2_b32 v[48:49], v9 offset0:165 offset1:173
	ds_read2_b32 v[50:51], v9 offset0:198 offset1:206
	ds_read2_b32 v[52:53], v9 offset0:231 offset1:239
	s_waitcnt lgkmcnt(6)
	v_cvt_pk_bf16_f32 v26, v32, v30
	s_waitcnt lgkmcnt(4)
	v_cvt_pk_bf16_f32 v27, v42, v44
	s_waitcnt lgkmcnt(2)
	v_cvt_pk_bf16_f32 v28, v46, v48
	s_waitcnt lgkmcnt(0)
	v_cvt_pk_bf16_f32 v29, v50, v52
	global_store_dwordx4 v[36:37], v[26:29], off
	v_cvt_pk_bf16_f32 v30, v33, v31
	v_cvt_pk_bf16_f32 v31, v43, v45
	v_cvt_pk_bf16_f32 v32, v47, v49
	v_cvt_pk_bf16_f32 v33, v51, v53
	ds_read2_b32 v[36:37], v9 offset0:16 offset1:24
	ds_read2_b32 v[42:43], v9 offset0:49 offset1:57
	ds_read2_b32 v[44:45], v9 offset0:82 offset1:90
	ds_read2_b32 v[46:47], v9 offset0:115 offset1:123
	ds_read2_b32 v[48:49], v9 offset0:148 offset1:156
	ds_read2_b32 v[50:51], v9 offset0:181 offset1:189
	ds_read2_b32 v[52:53], v9 offset0:214 offset1:222
	ds_read2_b32 v[54:55], v9 offset0:247 offset1:255
	v_lshlrev_b64 v[26:27], 11, v[66:67]
	v_lshl_add_u64 v[26:27], v[68:69], 0, v[26:27]
	global_store_dwordx4 v[26:27], v[30:33], off
	s_waitcnt lgkmcnt(6)
	v_cvt_pk_bf16_f32 v26, v36, v42
	s_waitcnt lgkmcnt(4)
	v_cvt_pk_bf16_f32 v27, v44, v46
	s_waitcnt lgkmcnt(2)
	v_cvt_pk_bf16_f32 v28, v48, v50
	s_waitcnt lgkmcnt(0)
	v_cvt_pk_bf16_f32 v29, v52, v54
	v_or_b32_e32 v30, s2, v7
	v_ashrrev_i32_e32 v31, 31, v30
	v_lshlrev_b64 v[30:31], 11, v[30:31]
	v_lshl_add_u64 v[30:31], v[68:69], 0, v[30:31]
	global_store_dwordx4 v[30:31], v[26:29], off
	v_or_b32_e32 v30, s2, v8
	v_ashrrev_i32_e32 v31, 31, v30
	v_lshlrev_b64 v[30:31], 11, v[30:31]
	v_lshl_add_u64 v[30:31], v[68:69], 0, v[30:31]
	v_cvt_pk_bf16_f32 v26, v37, v43
	v_cvt_pk_bf16_f32 v27, v45, v47
	v_cvt_pk_bf16_f32 v28, v49, v51
	v_cvt_pk_bf16_f32 v29, v53, v55
	global_store_dwordx4 v[30:31], v[26:29], off
	s_waitcnt lgkmcnt(0)
	s_branch .LBB0_89

; template <int NR>
; __device__ __forceinline__ void norm_group(int m0, const float* src_lat, const float* src_ctx, bf16* H, const float* gain, const float* mod, int shoff, int scoff, int lane, const float* part, float* ctx_out) {
;     const float* xr = (m0 < MLAT) ? src_lat + (size_t)m0 * D : src_ctx + (size_t)(m0 - MLAT) * D;
;     const int b = (m0 < MLAT) ? (m0 >> 13) : 4;
;     f32x4 v[NR][4]; float rstd[NR];
; #pragma unroll
;     for (int i = 0; i < NR; ++i)
; #pragma unroll
;         for (int j = 0; j < 4; ++j) v[i][j] = *((const f32x4*)(xr + (size_t)i * D) + lane + 64 * j);
;     if (part && m0 >= MLAT) {
; #pragma unroll
;         for (int i = 0; i < NR; ++i)
; #pragma unroll
;             for (int j = 0; j < 4; ++j) { const size_t o = (size_t)(m0 - MLAT + i) * D + 4 * (lane + 64 * j);
;                 const f32x4 p0 = *(const f32x4*)(part + o), p1 = *(const f32x4*)(part + (size_t)MCTX * D + o), p2 = *(const f32x4*)(part + (size_t)2 * MCTX * D + o), p3 = *(const f32x4*)(part + (size_t)3 * MCTX * D + o);
;                 v[i][j] = v[i][j] + ((p0 + p1) + (p2 + p3)); *(f32x4*)(ctx_out + o) = v[i][j]; }
;     }
; #pragma unroll
;     for (int i = 0; i < NR; ++i) { float s = 0.f;
; #pragma unroll
;         for (int j = 0; j < 4; ++j) s += (v[i][j].x * v[i][j].x + v[i][j].y * v[i][j].y) + (v[i][j].z * v[i][j].z + v[i][j].w * v[i][j].w);
;         rstd[i] = 1.0f / sqrtf(wave_sum(s) * (1.f / D) + EPS); }
.LBB0_110:
	s_ashr_i32 s9, s8, 31
	s_lshl_b64 s[0:1], s[8:9], 12
	v_lshl_add_u64 v[6:7], v[36:37], 0, s[0:1]
	global_load_dwordx4 v[70:73], v[6:7], off nt
	global_load_dwordx4 v[54:57], v[6:7], off offset:1024 nt
	global_load_dwordx4 v[30:33], v[6:7], off offset:2048 nt
	global_load_dwordx4 v[14:17], v[6:7], off offset:3072 nt
	v_add_co_u32_e32 v2, vcc, 0x1000, v6
	s_waitcnt vmcnt(3)
	v_pk_mul_f32 v[96:97], v[72:73], v[72:73]
	v_addc_co_u32_e32 v3, vcc, 0, v7, vcc
	global_load_dwordx4 v[66:69], v[2:3], off nt
	global_load_dwordx4 v[46:49], v[2:3], off offset:1024 nt
	global_load_dwordx4 v[18:21], v[2:3], off offset:2048 nt
	s_nop 0
	global_load_dwordx4 v[2:5], v[2:3], off offset:3072 nt
	v_pk_mul_f32 v[98:99], v[70:71], v[70:71]
	s_waitcnt vmcnt(4)
	v_mul_f32_e32 v38, v14, v14
	v_pk_mov_b32 v[100:101], v[98:99], v[96:97] op_sel:[1,0]
	v_mov_b32_e32 v99, v97
	v_pk_add_f32 v[96:97], v[100:101], v[98:99]
	v_pk_mul_f32 v[98:99], v[56:57], v[56:57]
	v_pk_mul_f32 v[100:101], v[54:55], v[54:55]
	v_mul_f32_e32 v39, v15, v15
	v_pk_mov_b32 v[102:103], v[100:101], v[98:99] op_sel:[1,0]
	v_mov_b32_e32 v101, v99
	v_pk_add_f32 v[98:99], v[102:103], v[100:101]
	v_pk_add_f32 v[96:97], v[96:97], v[96:97] op_sel:[0,1] op_sel_hi:[1,0]
	v_pk_add_f32 v[98:99], v[98:99], v[98:99] op_sel:[0,1] op_sel_hi:[1,0]
	v_mov_b32_e32 v97, v38
	v_mov_b32_e32 v99, v39
	v_mul_f32_e32 v80, v31, v31
	v_pk_add_f32 v[96:97], v[96:97], v[98:99]
	v_pk_fma_f32 v[98:99], v[30:31], v[30:31], v[80:81] op_sel_hi:[1,1,0]
	v_mul_f32_e32 v80, v33, v33
	v_mul_f32_e32 v40, v16, v16
	v_mul_f32_e32 v41, v17, v17
	v_pk_fma_f32 v[100:101], v[32:33], v[32:33], v[80:81] op_sel_hi:[1,1,0]
	v_mov_b32_e32 v99, v40
	v_mov_b32_e32 v101, v41
	v_pk_add_f32 v[98:99], v[98:99], v[100:101]
	v_add_co_u32_e32 v8, vcc, s96, v6
	v_pk_add_f32 v[96:97], v[96:97], v[98:99]
	s_nop 0
	v_addc_co_u32_e32 v9, vcc, 0, v7, vcc
	v_add_f32_e32 v38, v96, v97
	ds_bpermute_b32 v39, v89, v38
	v_add_co_u32_e32 v6, vcc, s87, v6
	s_waitcnt lgkmcnt(0)
	v_add_f32_e32 v38, v38, v39
	ds_bpermute_b32 v39, v90, v38
	v_addc_co_u32_e32 v7, vcc, 0, v7, vcc
	global_load_dwordx4 v[62:65], v[6:7], off offset:-4096 nt
	global_load_dwordx4 v[50:53], v[8:9], off offset:1024 nt
	global_load_dwordx4 v[26:29], v[8:9], off offset:2048 nt
	global_load_dwordx4 v[10:13], v[8:9], off offset:3072 nt
	global_load_dwordx4 v[58:61], v[6:7], off nt
	global_load_dwordx4 v[42:45], v[6:7], off offset:1024 nt
	global_load_dwordx4 v[22:25], v[6:7], off offset:2048 nt
	s_nop 0
	global_load_dwordx4 v[6:9], v[6:7], off offset:3072 nt
	s_waitcnt lgkmcnt(0)
	v_add_f32_e32 v38, v38, v39
	ds_bpermute_b32 v39, v91, v38
	s_waitcnt lgkmcnt(0)
	v_add_f32_e32 v38, v38, v39
	ds_bpermute_b32 v39, v92, v38
	s_waitcnt lgkmcnt(0)
	v_add_f32_e32 v38, v38, v39
	ds_bpermute_b32 v39, v93, v38
	s_waitcnt lgkmcnt(0)
	v_add_f32_e32 v38, v38, v39
	ds_bpermute_b32 v39, v94, v38
	s_waitcnt lgkmcnt(0)
	v_add_f32_e32 v38, v38, v39
	v_fmamk_f32 v38, v38, 0x3a800000, v205
	v_cmp_gt_f32_e32 vcc, s88, v38
	v_mul_f32_e32 v39, 0x4f800000, v38
	s_waitcnt vmcnt(11)
	v_pk_mul_f32 v[96:97], v[68:69], v[68:69]
	v_cndmask_b32_e32 v38, v38, v39, vcc
	v_sqrt_f32_e32 v39, v38
	v_pk_mul_f32 v[98:99], v[66:67], v[66:67]
	s_waitcnt vmcnt(9)
	v_mul_f32_e32 v82, v19, v19
	v_pk_mov_b32 v[100:101], v[98:99], v[96:97] op_sel:[1,0]
	v_add_u32_e32 v40, -1, v39
	v_fma_f32 v41, -v40, v39, v38
	v_cmp_ge_f32_e64 s[0:1], 0, v41
	v_add_u32_e32 v41, 1, v39
	v_mov_b32_e32 v99, v97
	v_cndmask_b32_e64 v40, v39, v40, s[0:1]
	v_fma_f32 v39, -v41, v39, v38
	v_cmp_lt_f32_e64 s[0:1], 0, v39
	v_pk_add_f32 v[96:97], v[100:101], v[98:99]
	v_pk_mul_f32 v[98:99], v[48:49], v[48:49]
	v_cndmask_b32_e64 v39, v40, v41, s[0:1]
	v_mul_f32_e32 v40, 0x37800000, v39
	v_cndmask_b32_e32 v39, v39, v40, vcc
	v_cmp_class_f32_e32 vcc, v38, v206
	v_pk_mul_f32 v[100:101], v[46:47], v[46:47]
	v_pk_add_f32 v[96:97], v[96:97], v[96:97] op_sel:[0,1] op_sel_hi:[1,0]
	v_cndmask_b32_e32 v38, v39, v38, vcc
	v_div_scale_f32 v39, s[0:1], v38, v38, 1.0
	v_rcp_f32_e32 v40, v39
	v_pk_mov_b32 v[102:103], v[100:101], v[98:99] op_sel:[1,0]
	v_mov_b32_e32 v101, v99
	v_pk_add_f32 v[98:99], v[102:103], v[100:101]
	v_fma_f32 v41, -v39, v40, 1.0
	v_fmac_f32_e32 v40, v41, v40
	v_div_scale_f32 v41, vcc, 1.0, v38, 1.0
	v_mul_f32_e32 v77, v41, v40
	v_fma_f32 v80, -v39, v77, v41
	v_fmac_f32_e32 v77, v80, v40
	v_fma_f32 v39, -v39, v77, v41
	v_div_fmas_f32 v39, v39, v40, v77
	v_div_fixup_f32 v80, v39, v38, 1.0
	s_waitcnt vmcnt(8)
	v_mul_f32_e32 v38, v2, v2
	v_mul_f32_e32 v39, v3, v3
	v_pk_add_f32 v[98:99], v[98:99], v[98:99] op_sel:[0,1] op_sel_hi:[1,0]
	v_mov_b32_e32 v97, v38
	v_mov_b32_e32 v99, v39
	v_pk_add_f32 v[96:97], v[96:97], v[98:99]
	v_pk_fma_f32 v[98:99], v[18:19], v[18:19], v[82:83] op_sel_hi:[1,1,0]
	v_mul_f32_e32 v82, v21, v21
	v_mul_f32_e32 v40, v4, v4
	v_mul_f32_e32 v41, v5, v5
	v_pk_fma_f32 v[100:101], v[20:21], v[20:21], v[82:83] op_sel_hi:[1,1,0]
	v_mov_b32_e32 v99, v40
	v_mov_b32_e32 v101, v41
	v_pk_add_f32 v[98:99], v[98:99], v[100:101]
	s_waitcnt vmcnt(5)
	v_mul_f32_e32 v84, v27, v27
	v_pk_add_f32 v[96:97], v[96:97], v[98:99]
	v_pk_mul_f32 v[98:99], v[62:63], v[62:63]
	v_add_f32_e32 v38, v96, v97
	ds_bpermute_b32 v39, v89, v38
	v_pk_mul_f32 v[96:97], v[64:65], v[64:65]
	s_waitcnt vmcnt(1)
	v_mul_f32_e32 v86, v23, v23
	v_pk_mov_b32 v[100:101], v[98:99], v[96:97] op_sel:[1,0]
	v_mov_b32_e32 v99, v97
	s_waitcnt lgkmcnt(0)
	v_add_f32_e32 v38, v38, v39
	ds_bpermute_b32 v39, v90, v38
	v_pk_add_f32 v[96:97], v[100:101], v[98:99]
	v_pk_mul_f32 v[98:99], v[52:53], v[52:53]
	v_pk_mul_f32 v[100:101], v[50:51], v[50:51]
	v_pk_add_f32 v[96:97], v[96:97], v[96:97] op_sel:[0,1] op_sel_hi:[1,0]
	s_waitcnt lgkmcnt(0)
; template <int NR>
; __device__ __forceinline__ void norm_group(int m0, const float* src_lat, const float* src_ctx, bf16* H, const float* gain, const float* mod, int shoff, int scoff, int lane, const float* part, float* ctx_out) {
;     ...
; #pragma unroll
;     for (int i = 0; i < NR; ++i) { float s = 0.f;
; #pragma unroll
;         for (int j = 0; j < 4; ++j) s += (v[i][j].x * v[i][j].x + v[i][j].y * v[i][j].y) + (v[i][j].z * v[i][j].z + v[i][j].w * v[i][j].w);
;         rstd[i] = 1.0f / sqrtf(wave_sum(s) * (1.f / D) + EPS); }
	v_add_f32_e32 v38, v38, v39
	ds_bpermute_b32 v39, v91, v38
	v_pk_mov_b32 v[102:103], v[100:101], v[98:99] op_sel:[1,0]
	v_mov_b32_e32 v101, v99
	v_pk_add_f32 v[98:99], v[102:103], v[100:101]
	v_pk_mul_f32 v[70:71], v[70:71], v[80:81] op_sel_hi:[1,0]
	s_waitcnt lgkmcnt(0)
	v_add_f32_e32 v38, v38, v39
	ds_bpermute_b32 v39, v92, v38
	v_pk_add_f32 v[98:99], v[98:99], v[98:99] op_sel:[0,1] op_sel_hi:[1,0]
	v_pk_mul_f32 v[72:73], v[72:73], v[80:81] op_sel_hi:[1,0]
	v_pk_mul_f32 v[54:55], v[54:55], v[80:81] op_sel_hi:[1,0]
	v_pk_mul_f32 v[56:57], v[56:57], v[80:81] op_sel_hi:[1,0]
	s_waitcnt lgkmcnt(0)
	v_add_f32_e32 v38, v38, v39
	ds_bpermute_b32 v39, v93, v38
	v_pk_mul_f32 v[30:31], v[30:31], v[80:81] op_sel_hi:[1,0]
	v_pk_mul_f32 v[32:33], v[32:33], v[80:81] op_sel_hi:[1,0]
	v_pk_mul_f32 v[14:15], v[14:15], v[80:81] op_sel_hi:[1,0]
	v_pk_mul_f32 v[16:17], v[16:17], v[80:81] op_sel_hi:[1,0]
	s_waitcnt lgkmcnt(0)
	v_add_f32_e32 v38, v38, v39
	ds_bpermute_b32 v39, v94, v38
	s_waitcnt lgkmcnt(0)
	v_add_f32_e32 v38, v38, v39
	v_fmamk_f32 v38, v38, 0x3a800000, v205
	v_cmp_gt_f32_e32 vcc, s88, v38
	v_mul_f32_e32 v39, 0x4f800000, v38
	s_nop 0
	v_cndmask_b32_e32 v38, v38, v39, vcc
	v_sqrt_f32_e32 v39, v38
	s_nop 0
	v_add_u32_e32 v40, -1, v39
	v_fma_f32 v41, -v40, v39, v38
	v_cmp_ge_f32_e64 s[0:1], 0, v41
	v_add_u32_e32 v41, 1, v39
	s_nop 0
	v_cndmask_b32_e64 v40, v39, v40, s[0:1]
	v_fma_f32 v39, -v41, v39, v38
	v_cmp_lt_f32_e64 s[0:1], 0, v39
	s_nop 1
	v_cndmask_b32_e64 v39, v40, v41, s[0:1]
	v_mul_f32_e32 v40, 0x37800000, v39
	v_cndmask_b32_e32 v39, v39, v40, vcc
	v_cmp_class_f32_e32 vcc, v38, v206
	s_nop 1
	v_cndmask_b32_e32 v38, v39, v38, vcc
	v_div_scale_f32 v39, s[0:1], v38, v38, 1.0
	v_rcp_f32_e32 v40, v39
	s_nop 0
	v_fma_f32 v41, -v39, v40, 1.0
	v_fmac_f32_e32 v40, v41, v40
	v_div_scale_f32 v41, vcc, 1.0, v38, 1.0
	v_mul_f32_e32 v77, v41, v40
	v_fma_f32 v82, -v39, v77, v41
	v_fmac_f32_e32 v77, v82, v40
	v_fma_f32 v39, -v39, v77, v41
	v_div_fmas_f32 v39, v39, v40, v77
	v_div_fixup_f32 v82, v39, v38, 1.0
	v_mul_f32_e32 v38, v10, v10
	v_mul_f32_e32 v39, v11, v11
	v_mov_b32_e32 v97, v38
	v_mov_b32_e32 v99, v39
	v_pk_add_f32 v[96:97], v[96:97], v[98:99]
	v_pk_fma_f32 v[98:99], v[26:27], v[26:27], v[84:85] op_sel_hi:[1,1,0]
	v_mul_f32_e32 v84, v29, v29
	v_mul_f32_e32 v40, v12, v12
	v_mul_f32_e32 v41, v13, v13
	v_pk_fma_f32 v[100:101], v[28:29], v[28:29], v[84:85] op_sel_hi:[1,1,0]
	v_mov_b32_e32 v99, v40
	v_mov_b32_e32 v101, v41
	v_pk_add_f32 v[98:99], v[98:99], v[100:101]
	v_pk_mul_f32 v[66:67], v[66:67], v[82:83] op_sel_hi:[1,0]
	v_pk_add_f32 v[96:97], v[96:97], v[98:99]
	v_pk_mul_f32 v[98:99], v[58:59], v[58:59]
	v_add_f32_e32 v38, v96, v97
	ds_bpermute_b32 v39, v89, v38
	v_pk_mul_f32 v[96:97], v[60:61], v[60:61]
	v_pk_mul_f32 v[68:69], v[68:69], v[82:83] op_sel_hi:[1,0]
	v_pk_mov_b32 v[100:101], v[98:99], v[96:97] op_sel:[1,0]
	v_mov_b32_e32 v99, v97
	s_waitcnt lgkmcnt(0)
	v_add_f32_e32 v38, v38, v39
	ds_bpermute_b32 v39, v90, v38
	v_pk_add_f32 v[96:97], v[100:101], v[98:99]
	v_pk_mul_f32 v[98:99], v[44:45], v[44:45]
	v_pk_mul_f32 v[100:101], v[42:43], v[42:43]
	v_pk_add_f32 v[96:97], v[96:97], v[96:97] op_sel:[0,1] op_sel_hi:[1,0]
	s_waitcnt lgkmcnt(0)
	v_add_f32_e32 v38, v38, v39
	ds_bpermute_b32 v39, v91, v38
	v_pk_mov_b32 v[102:103], v[100:101], v[98:99] op_sel:[1,0]
	v_mov_b32_e32 v101, v99
	v_pk_add_f32 v[98:99], v[102:103], v[100:101]
	v_pk_mul_f32 v[46:47], v[46:47], v[82:83] op_sel_hi:[1,0]
	s_waitcnt lgkmcnt(0)
	v_add_f32_e32 v38, v38, v39
	ds_bpermute_b32 v39, v92, v38
	v_pk_add_f32 v[98:99], v[98:99], v[98:99] op_sel:[0,1] op_sel_hi:[1,0]
	v_pk_mul_f32 v[48:49], v[48:49], v[82:83] op_sel_hi:[1,0]
	v_pk_mul_f32 v[18:19], v[18:19], v[82:83] op_sel_hi:[1,0]
	v_pk_mul_f32 v[20:21], v[20:21], v[82:83] op_sel_hi:[1,0]
	s_waitcnt lgkmcnt(0)
	v_add_f32_e32 v38, v38, v39
	ds_bpermute_b32 v39, v93, v38
	v_pk_mul_f32 v[2:3], v[2:3], v[82:83] op_sel_hi:[1,0]
	v_pk_mul_f32 v[4:5], v[4:5], v[82:83] op_sel_hi:[1,0]
	s_waitcnt lgkmcnt(0)
	v_add_f32_e32 v38, v38, v39
	ds_bpermute_b32 v39, v94, v38
	s_waitcnt lgkmcnt(0)
	v_add_f32_e32 v38, v38, v39
	v_fmamk_f32 v38, v38, 0x3a800000, v205
	v_cmp_gt_f32_e32 vcc, s88, v38
	v_mul_f32_e32 v39, 0x4f800000, v38
	s_nop 0
	v_cndmask_b32_e32 v38, v38, v39, vcc
	v_sqrt_f32_e32 v39, v38
	s_nop 0
	v_add_u32_e32 v40, -1, v39
	v_fma_f32 v41, -v40, v39, v38
	v_cmp_ge_f32_e64 s[0:1], 0, v41
	v_add_u32_e32 v41, 1, v39
	s_nop 0
	v_cndmask_b32_e64 v40, v39, v40, s[0:1]
	v_fma_f32 v39, -v41, v39, v38
	v_cmp_lt_f32_e64 s[0:1], 0, v39
	s_nop 1
	v_cndmask_b32_e64 v39, v40, v41, s[0:1]
	v_mul_f32_e32 v40, 0x37800000, v39
	v_cndmask_b32_e32 v39, v39, v40, vcc
	v_cmp_class_f32_e32 vcc, v38, v206
	s_nop 1
	v_cndmask_b32_e32 v38, v39, v38, vcc
	v_div_scale_f32 v39, s[0:1], v38, v38, 1.0
	v_rcp_f32_e32 v40, v39
	s_nop 0
	v_fma_f32 v41, -v39, v40, 1.0
	v_fmac_f32_e32 v40, v41, v40
	v_div_scale_f32 v41, vcc, 1.0, v38, 1.0
	v_mul_f32_e32 v77, v41, v40
	v_fma_f32 v84, -v39, v77, v41
	v_fmac_f32_e32 v77, v84, v40
	v_fma_f32 v39, -v39, v77, v41
	v_div_fmas_f32 v39, v39, v40, v77
	v_div_fixup_f32 v84, v39, v38, 1.0
	s_waitcnt vmcnt(0)
	v_mul_f32_e32 v38, v6, v6
	v_mul_f32_e32 v39, v7, v7
	v_mov_b32_e32 v97, v38
	v_mov_b32_e32 v99, v39
	v_pk_add_f32 v[96:97], v[96:97], v[98:99]
	v_pk_fma_f32 v[98:99], v[22:23], v[22:23], v[86:87] op_sel_hi:[1,1,0]
	v_mul_f32_e32 v86, v25, v25
	v_mul_f32_e32 v40, v8, v8
	v_mul_f32_e32 v41, v9, v9
	v_pk_fma_f32 v[100:101], v[24:25], v[24:25], v[86:87] op_sel_hi:[1,1,0]
	v_mov_b32_e32 v99, v40
	v_mov_b32_e32 v101, v41
	v_pk_add_f32 v[98:99], v[98:99], v[100:101]
	v_pk_mul_f32 v[62:63], v[62:63], v[84:85] op_sel_hi:[1,0]
	v_pk_add_f32 v[96:97], v[96:97], v[98:99]
	v_pk_mul_f32 v[64:65], v[64:65], v[84:85] op_sel_hi:[1,0]
	v_add_f32_e32 v38, v96, v97
	ds_bpermute_b32 v39, v89, v38
	s_waitcnt lgkmcnt(0)
; __device__ __forceinline__ unsigned pk2(float lo, float hi) { return cvtpk(lo, hi); }
; template <int NR>
; __device__ __forceinline__ void norm_group(int m0, const float* src_lat, const float* src_ctx, bf16* H, const float* gain, const float* mod, int shoff, int scoff, int lane, const float* part, float* ctx_out) {
;     ...
; #pragma unroll
;     for (int i = 0; i < NR; ++i) { float s = 0.f;
; #pragma unroll
;         for (int j = 0; j < 4; ++j) s += (v[i][j].x * v[i][j].x + v[i][j].y * v[i][j].y) + (v[i][j].z * v[i][j].z + v[i][j].w * v[i][j].w);
;         rstd[i] = 1.0f / sqrtf(wave_sum(s) * (1.f / D) + EPS); }
;     const float* mr = mod + b * 6144;
; #pragma unroll
;     for (int j = 0; j < 4; ++j) { const int idx = 4 * (lane + 64 * j);
;         const f32x4 g = *(const f32x4*)(gain + idx), sc = *(const f32x4*)(mr + scoff + idx), sh = *(const f32x4*)(mr + shoff + idx);
;         const f32x4 gs = g * (1.f + sc);
; #pragma unroll
;         for (int i = 0; i < NR; ++i) { const f32x4 y = v[i][j] * rstd[i] * gs + sh;
;             v2u o; o.x = pk2(y.x, y.y); o.y = pk2(y.z, y.w);
;             *(v2u*)(H + (size_t)(m0 + i) * D + idx) = o; } }
	v_add_f32_e32 v38, v38, v39
	ds_bpermute_b32 v39, v90, v38
	s_waitcnt lgkmcnt(0)
	v_add_f32_e32 v38, v38, v39
	ds_bpermute_b32 v39, v91, v38
	s_waitcnt lgkmcnt(0)
	v_add_f32_e32 v38, v38, v39
	ds_bpermute_b32 v39, v92, v38
	s_waitcnt lgkmcnt(0)
	v_add_f32_e32 v38, v38, v39
	ds_bpermute_b32 v39, v93, v38
	s_waitcnt lgkmcnt(0)
	v_add_f32_e32 v38, v38, v39
	ds_bpermute_b32 v39, v94, v38
	s_waitcnt lgkmcnt(0)
	v_add_f32_e32 v38, v38, v39
	v_fmamk_f32 v38, v38, 0x3a800000, v205
	v_cmp_gt_f32_e32 vcc, s88, v38
	v_mul_f32_e32 v39, 0x4f800000, v38
	s_nop 0
	v_cndmask_b32_e32 v38, v38, v39, vcc
	v_sqrt_f32_e32 v39, v38
	s_nop 0
	v_add_u32_e32 v40, -1, v39
	v_fma_f32 v41, -v40, v39, v38
	v_cmp_ge_f32_e64 s[0:1], 0, v41
	v_add_u32_e32 v41, 1, v39
	s_nop 0
	v_cndmask_b32_e64 v40, v39, v40, s[0:1]
	v_fma_f32 v39, -v41, v39, v38
	v_cmp_lt_f32_e64 s[0:1], 0, v39
	s_nop 1
	v_cndmask_b32_e64 v39, v40, v41, s[0:1]
	v_mul_f32_e32 v40, 0x37800000, v39
	v_cndmask_b32_e32 v39, v39, v40, vcc
	v_cmp_class_f32_e32 vcc, v38, v206
	s_nop 1
	v_cndmask_b32_e32 v38, v39, v38, vcc
	v_div_scale_f32 v39, s[0:1], v38, v38, 1.0
	s_lshr_b32 s0, s20, 11
	s_mulk_i32 s0, 0x1800
	s_ashr_i32 s1, s0, 31
	s_lshl_b64 s[0:1], s[0:1], 2
	s_add_u32 s0, s21, s0
	s_addc_u32 s1, s22, s1
	s_add_u32 s2, s0, 0x1000
	s_addc_u32 s3, s1, 0
	global_load_dwordx4 v[96:99], v[78:79], off nt
	global_load_dwordx4 v[100:103], v76, s[2:3] nt
	global_load_dwordx4 v[104:107], v76, s[0:1] nt
	v_rcp_f32_e32 v40, v39
	s_add_i32 s10, s8, 1
	s_add_i32 s12, s8, 2
	s_add_i32 s16, s8, 3
	v_fma_f32 v41, -v39, v40, 1.0
	v_fmac_f32_e32 v40, v41, v40
	v_div_scale_f32 v41, vcc, 1.0, v38, 1.0
	v_mul_f32_e32 v77, v41, v40
	v_fma_f32 v86, -v39, v77, v41
	v_fmac_f32_e32 v77, v86, v40
	v_fma_f32 v39, -v39, v77, v41
	v_div_fmas_f32 v39, v39, v40, v77
	v_div_fixup_f32 v86, v39, v38, 1.0
	s_ashr_i32 s11, s10, 31
	s_ashr_i32 s13, s12, 31
	v_pk_mul_f32 v[58:59], v[58:59], v[86:87] op_sel_hi:[1,0]
	v_pk_mul_f32 v[60:61], v[60:61], v[86:87] op_sel_hi:[1,0]
	s_ashr_i32 s17, s16, 31
	s_lshl_b64 s[18:19], s[8:9], 11
	s_lshl_b64 s[10:11], s[10:11], 11
	s_lshl_b64 s[12:13], s[12:13], 11
	s_lshl_b64 s[16:17], s[16:17], 11
	v_lshlrev_b32_e32 v38, 1, v85
	v_pk_mul_f32 v[42:43], v[42:43], v[86:87] op_sel_hi:[1,0]
	v_pk_mul_f32 v[44:45], v[44:45], v[86:87] op_sel_hi:[1,0]
	s_waitcnt vmcnt(1)
	v_pk_add_f32 v[102:103], v[102:103], 1.0 op_sel_hi:[1,0]
	v_pk_add_f32 v[100:101], v[100:101], 1.0 op_sel_hi:[1,0]
	v_pk_mul_f32 v[98:99], v[98:99], v[102:103]
	v_pk_mul_f32 v[96:97], v[96:97], v[100:101]
	s_waitcnt vmcnt(0)
	v_pk_fma_f32 v[72:73], v[72:73], v[98:99], v[106:107]
	v_pk_fma_f32 v[70:71], v[70:71], v[96:97], v[104:105]
	v_pk_fma_f32 v[68:69], v[68:69], v[98:99], v[106:107]
	v_pk_fma_f32 v[66:67], v[66:67], v[96:97], v[104:105]
	v_pk_fma_f32 v[64:65], v[64:65], v[98:99], v[106:107]
	v_pk_fma_f32 v[62:63], v[62:63], v[96:97], v[104:105]
	v_pk_fma_f32 v[60:61], v[98:99], v[60:61], v[106:107]
	v_pk_fma_f32 v[58:59], v[96:97], v[58:59], v[104:105]
	v_cvt_pk_bf16_f32 v70, v70, v71
	v_cvt_pk_bf16_f32 v71, v72, v73
	v_lshl_add_u64 v[72:73], v[74:75], 0, s[18:19]
	v_cvt_pk_bf16_f32 v66, v66, v67
	v_cvt_pk_bf16_f32 v67, v68, v69
	v_lshl_add_u64 v[68:69], v[74:75], 0, s[10:11]
	v_cvt_pk_bf16_f32 v62, v62, v63
	v_cvt_pk_bf16_f32 v63, v64, v65
	v_lshl_add_u64 v[64:65], v[74:75], 0, s[12:13]
	v_cvt_pk_bf16_f32 v58, v58, v59
	v_cvt_pk_bf16_f32 v59, v60, v61
	v_lshl_add_u64 v[60:61], v[74:75], 0, s[16:17]
	global_store_dwordx2 v[72:73], v[70:71], off
	global_store_dwordx2 v[68:69], v[66:67], off
	global_store_dwordx2 v[64:65], v[62:63], off
	global_store_dwordx2 v[60:61], v[58:59], off
	v_lshlrev_b32_e32 v62, 2, v85
	global_load_dwordx4 v[58:61], v[78:79], off offset:1024 nt
	s_nop 0
	global_load_dwordx4 v[62:65], v62, s[2:3] nt
	s_nop 0
	global_load_dwordx4 v[66:69], v76, s[0:1] offset:1024 nt
	s_add_u32 s18, s90, s18
	s_addc_u32 s19, s91, s19
	s_add_u32 s10, s90, s10
	s_addc_u32 s11, s91, s11
	s_add_u32 s12, s90, s12
	s_addc_u32 s13, s91, s13
	s_add_u32 s16, s90, s16
	s_addc_u32 s17, s91, s17
	s_add_i32 s20, s20, s52
	s_add_i32 s8, s8, s59
	s_cmpk_gt_i32 s20, 0x1fff
	s_waitcnt vmcnt(1)
; __device__ __forceinline__ unsigned pk2(float lo, float hi) { return cvtpk(lo, hi); }
; template <int NR>
; __device__ __forceinline__ void norm_group(int m0, const float* src_lat, const float* src_ctx, bf16* H, const float* gain, const float* mod, int shoff, int scoff, int lane, const float* part, float* ctx_out) {
;     ...
;     const float* mr = mod + b * 6144;
; #pragma unroll
;     for (int j = 0; j < 4; ++j) { const int idx = 4 * (lane + 64 * j);
;         const f32x4 g = *(const f32x4*)(gain + idx), sc = *(const f32x4*)(mr + scoff + idx), sh = *(const f32x4*)(mr + shoff + idx);
;         const f32x4 gs = g * (1.f + sc);
; #pragma unroll
;         for (int i = 0; i < NR; ++i) { const f32x4 y = v[i][j] * rstd[i] * gs + sh;
;             v2u o; o.x = pk2(y.x, y.y); o.y = pk2(y.z, y.w);
;             *(v2u*)(H + (size_t)(m0 + i) * D + idx) = o; } }
	v_pk_add_f32 v[62:63], v[62:63], 1.0 op_sel_hi:[1,0]
	v_pk_add_f32 v[64:65], v[64:65], 1.0 op_sel_hi:[1,0]
	v_pk_mul_f32 v[58:59], v[58:59], v[62:63]
	v_pk_mul_f32 v[60:61], v[60:61], v[64:65]
	s_waitcnt vmcnt(0)
	v_pk_fma_f32 v[46:47], v[46:47], v[58:59], v[66:67]
	v_pk_fma_f32 v[48:49], v[48:49], v[60:61], v[68:69]
	v_cvt_pk_bf16_f32 v46, v46, v47
	v_pk_fma_f32 v[54:55], v[54:55], v[58:59], v[66:67]
	v_cvt_pk_bf16_f32 v47, v48, v49
	global_store_dwordx2 v38, v[46:47], s[10:11]
	v_pk_mul_f32 v[46:47], v[50:51], v[84:85] op_sel_hi:[1,0]
	v_pk_mul_f32 v[48:49], v[52:53], v[84:85] op_sel_hi:[1,0]
	v_pk_fma_f32 v[46:47], v[46:47], v[58:59], v[66:67]
	v_pk_fma_f32 v[42:43], v[42:43], v[58:59], v[66:67]
	v_pk_fma_f32 v[56:57], v[56:57], v[60:61], v[68:69]
	v_cvt_pk_bf16_f32 v54, v54, v55
	v_pk_fma_f32 v[48:49], v[48:49], v[60:61], v[68:69]
	v_cvt_pk_bf16_f32 v55, v56, v57
	global_store_dwordx2 v38, v[54:55], s[18:19]
	v_cvt_pk_bf16_f32 v46, v46, v47
	v_cvt_pk_bf16_f32 v47, v48, v49
	global_store_dwordx2 v38, v[46:47], s[12:13]
	v_pk_fma_f32 v[44:45], v[44:45], v[60:61], v[68:69]
	v_cvt_pk_bf16_f32 v42, v42, v43
	s_nop 0
	v_cvt_pk_bf16_f32 v43, v44, v45
	global_store_dwordx2 v38, v[42:43], s[16:17]
	v_lshlrev_b32_e32 v38, 2, v87
	global_load_dwordx4 v[42:45], v[78:79], off offset:2048 nt
	global_load_dwordx4 v[46:49], v38, s[2:3] nt
	global_load_dwordx4 v[50:53], v76, s[0:1] offset:2048 nt
	s_waitcnt vmcnt(1)
	v_pk_add_f32 v[48:49], v[48:49], 1.0 op_sel_hi:[1,0]
	v_pk_add_f32 v[46:47], v[46:47], 1.0 op_sel_hi:[1,0]
	v_pk_mul_f32 v[44:45], v[44:45], v[48:49]
	v_pk_mul_f32 v[42:43], v[42:43], v[46:47]
	s_waitcnt vmcnt(0)
	v_pk_fma_f32 v[32:33], v[32:33], v[44:45], v[52:53]
	v_pk_fma_f32 v[30:31], v[30:31], v[42:43], v[50:51]
	v_pk_fma_f32 v[18:19], v[18:19], v[42:43], v[50:51]
	v_cvt_pk_bf16_f32 v30, v30, v31
	v_cvt_pk_bf16_f32 v31, v32, v33
	v_lshlrev_b32_e32 v32, 1, v87
	v_pk_fma_f32 v[20:21], v[20:21], v[44:45], v[52:53]
	v_cvt_pk_bf16_f32 v18, v18, v19
	global_store_dwordx2 v32, v[30:31], s[18:19]
	v_cvt_pk_bf16_f32 v19, v20, v21
	global_store_dwordx2 v32, v[18:19], s[10:11]
	v_pk_mul_f32 v[18:19], v[26:27], v[84:85] op_sel_hi:[1,0]
	v_pk_mul_f32 v[20:21], v[28:29], v[84:85] op_sel_hi:[1,0]
	v_pk_fma_f32 v[18:19], v[18:19], v[42:43], v[50:51]
	v_pk_fma_f32 v[20:21], v[20:21], v[44:45], v[52:53]
	v_cvt_pk_bf16_f32 v18, v18, v19
	s_nop 0
	v_cvt_pk_bf16_f32 v19, v20, v21
	global_store_dwordx2 v32, v[18:19], s[12:13]
	v_pk_mul_f32 v[18:19], v[22:23], v[86:87] op_sel_hi:[1,0]
	v_pk_mul_f32 v[20:21], v[24:25], v[86:87] op_sel_hi:[1,0]
	v_pk_fma_f32 v[18:19], v[18:19], v[42:43], v[50:51]
	v_pk_fma_f32 v[20:21], v[20:21], v[44:45], v[52:53]
	v_cvt_pk_bf16_f32 v18, v18, v19
	v_lshlrev_b32_e32 v22, 2, v88
	v_cvt_pk_bf16_f32 v19, v20, v21
	global_store_dwordx2 v32, v[18:19], s[16:17]
	global_load_dwordx4 v[18:21], v[78:79], off offset:3072 nt
	s_nop 0
	global_load_dwordx4 v[22:25], v22, s[2:3] nt
	s_nop 0
	global_load_dwordx4 v[26:29], v76, s[0:1] offset:3072 nt
	s_waitcnt vmcnt(1)
	v_pk_add_f32 v[24:25], v[24:25], 1.0 op_sel_hi:[1,0]
	v_pk_add_f32 v[22:23], v[22:23], 1.0 op_sel_hi:[1,0]
	v_pk_mul_f32 v[20:21], v[20:21], v[24:25]
	v_pk_mul_f32 v[18:19], v[18:19], v[22:23]
	s_waitcnt vmcnt(0)
	v_pk_fma_f32 v[16:17], v[16:17], v[20:21], v[28:29]
	v_pk_fma_f32 v[14:15], v[14:15], v[18:19], v[26:27]
	v_pk_fma_f32 v[2:3], v[2:3], v[18:19], v[26:27]
	v_cvt_pk_bf16_f32 v14, v14, v15
	v_cvt_pk_bf16_f32 v15, v16, v17
	v_lshlrev_b32_e32 v16, 1, v88
	v_pk_fma_f32 v[4:5], v[4:5], v[20:21], v[28:29]
	v_cvt_pk_bf16_f32 v2, v2, v3
	global_store_dwordx2 v16, v[14:15], s[18:19]
	v_cvt_pk_bf16_f32 v3, v4, v5
	global_store_dwordx2 v16, v[2:3], s[10:11]
	v_pk_mul_f32 v[2:3], v[10:11], v[84:85] op_sel_hi:[1,0]
	v_pk_mul_f32 v[4:5], v[12:13], v[84:85] op_sel_hi:[1,0]
	v_pk_fma_f32 v[2:3], v[2:3], v[18:19], v[26:27]
	v_pk_fma_f32 v[4:5], v[4:5], v[20:21], v[28:29]
	v_cvt_pk_bf16_f32 v2, v2, v3
	s_nop 0
	v_cvt_pk_bf16_f32 v3, v4, v5
	global_store_dwordx2 v16, v[2:3], s[12:13]
	v_pk_mul_f32 v[2:3], v[6:7], v[86:87] op_sel_hi:[1,0]
	v_pk_mul_f32 v[4:5], v[8:9], v[86:87] op_sel_hi:[1,0]
	v_pk_fma_f32 v[2:3], v[2:3], v[18:19], v[26:27]
	v_pk_fma_f32 v[4:5], v[4:5], v[20:21], v[28:29]
	v_cvt_pk_bf16_f32 v2, v2, v3
	s_nop 0
	v_cvt_pk_bf16_f32 v3, v4, v5
	global_store_dwordx2 v16, v[2:3], s[16:17]
	s_cbranch_scc0 .LBB0_110

; __device__ __forceinline__ unsigned pk2(float lo, float hi) { return cvtpk(lo, hi); }
; template <int NR>
; __device__ __forceinline__ void norm_group(int m0, const float* src_lat, const float* src_ctx, bf16* H, const float* gain, const float* mod, int shoff, int scoff, int lane, const float* part, float* ctx_out) {
;     ...
; #pragma unroll
;     for (int i = 0; i < NR; ++i) { float s = 0.f;
; #pragma unroll
;         for (int j = 0; j < 4; ++j) s += (v[i][j].x * v[i][j].x + v[i][j].y * v[i][j].y) + (v[i][j].z * v[i][j].z + v[i][j].w * v[i][j].w);
;         rstd[i] = 1.0f / sqrtf(wave_sum(s) * (1.f / D) + EPS); }
;     const float* mr = mod + b * 6144;
; #pragma unroll
;     for (int j = 0; j < 4; ++j) { const int idx = 4 * (lane + 64 * j);
;         const f32x4 g = *(const f32x4*)(gain + idx), sc = *(const f32x4*)(mr + scoff + idx), sh = *(const f32x4*)(mr + shoff + idx);
;         const f32x4 gs = g * (1.f + sc);
; #pragma unroll
;         for (int i = 0; i < NR; ++i) { const f32x4 y = v[i][j] * rstd[i] * gs + sh;
;             v2u o; o.x = pk2(y.x, y.y); o.y = pk2(y.z, y.w);
;             *(v2u*)(H + (size_t)(m0 + i) * D + idx) = o; } }
; __device__ __forceinline__ void norm_pass(const float* src_lat, const float* src_ctx, bf16* H, const float* gain, const float* mod, int shoff, int scoff, int nrows, int lane, int wave, const float* part = nullptr, float* ctx_out = nullptr) {
;     ...
;     for (int m = MLAT + gw; m < nrows; m += NGW) norm_group<1>(m, src_lat, src_ctx, H, gain, mod, shoff, scoff, lane, part, ctx_out);
.LBB0_113:
	s_min_i32 s0, s6, 0x8000
	s_ashr_i32 s0, s0, 13
	s_waitcnt vmcnt(3)
	v_pk_mul_f32 v[36:37], v[16:17], v[16:17]
	v_pk_mul_f32 v[42:43], v[14:15], v[14:15]
	s_mulk_i32 s0, 0x1800
	s_waitcnt vmcnt(2)
	v_pk_mul_f32 v[30:31], v[12:13], v[12:13]
	v_pk_mul_f32 v[32:33], v[10:11], v[10:11]
	v_pk_mov_b32 v[44:45], v[42:43], v[36:37] op_sel:[1,0]
	v_mov_b32_e32 v43, v37
	s_ashr_i32 s1, s0, 31
	v_pk_add_f32 v[36:37], v[44:45], v[42:43]
	v_pk_mov_b32 v[42:43], v[32:33], v[30:31] op_sel:[1,0]
	v_mov_b32_e32 v33, v31
	s_lshl_b64 s[0:1], s[0:1], 2
	v_readlane_b32 s6, v255, 4
	v_pk_add_f32 v[30:31], v[42:43], v[32:33]
	s_add_u32 s6, s6, s0
	v_readlane_b32 s0, v255, 3
	v_pk_add_f32 v[46:47], v[30:31], v[30:31] op_sel_hi:[0,1]
	s_waitcnt vmcnt(1)
	v_mul_f32_e32 v30, v6, v6
	s_addc_u32 s7, s0, s1
	v_pk_fma_f32 v[42:43], v[6:7], v[6:7], v[30:31] op_sel_hi:[1,1,0]
	v_mul_f32_e32 v30, v8, v8
	s_add_u32 s18, s6, 0x1000
	v_pk_fma_f32 v[44:45], v[8:9], v[8:9], v[30:31] op_sel_hi:[1,1,0]
	s_addc_u32 s19, s7, 0
	v_pk_add_f32 v[36:37], v[36:37], v[36:37] op_sel_hi:[0,1]
	s_waitcnt vmcnt(0)
	v_mul_f32_e32 v42, v2, v2
	v_mul_f32_e32 v44, v3, v3
	global_load_dwordx4 v[30:33], v18, s[18:19] nt
	v_mul_f32_e32 v36, v4, v4
	v_mul_f32_e32 v46, v5, v5
	v_pk_add_f32 v[50:51], v[42:43], v[44:45]
	global_load_dwordx4 v[42:45], v[20:21], off nt
	v_pk_add_f32 v[36:37], v[36:37], v[46:47]
	global_load_dwordx4 v[46:49], v18, s[6:7] nt
	v_pk_add_f32 v[36:37], v[50:51], v[36:37]
	s_add_i32 s78, s78, s52
	v_add_f32_e32 v19, v36, v37
	ds_bpermute_b32 v36, v24, v19
	s_waitcnt lgkmcnt(0)
	v_add_f32_e32 v19, v19, v36
	ds_bpermute_b32 v36, v25, v19
	s_waitcnt lgkmcnt(0)
	v_add_f32_e32 v19, v19, v36
	ds_bpermute_b32 v36, v26, v19
	s_waitcnt lgkmcnt(0)
	v_add_f32_e32 v19, v19, v36
	ds_bpermute_b32 v36, v27, v19
	s_waitcnt lgkmcnt(0)
	v_add_f32_e32 v19, v19, v36
	ds_bpermute_b32 v36, v28, v19
	s_waitcnt lgkmcnt(0)
	v_add_f32_e32 v19, v19, v36
	ds_bpermute_b32 v36, v29, v19
	s_waitcnt lgkmcnt(0)
	v_add_f32_e32 v19, v19, v36
	v_fmamk_f32 v19, v19, 0x3a800000, v205
	v_mul_f32_e32 v36, 0x4f800000, v19
	v_cmp_gt_f32_e32 vcc, s88, v19
	s_waitcnt vmcnt(2)
	v_pk_add_f32 v[30:31], v[30:31], 1.0 op_sel_hi:[1,0]
	v_cndmask_b32_e32 v19, v19, v36, vcc
	v_sqrt_f32_e32 v36, v19
	v_pk_add_f32 v[32:33], v[32:33], 1.0 op_sel_hi:[1,0]
	s_waitcnt vmcnt(1)
	v_pk_mul_f32 v[30:31], v[42:43], v[30:31]
	v_pk_mul_f32 v[32:33], v[44:45], v[32:33]
	v_add_u32_e32 v37, -1, v36
	v_add_u32_e32 v38, 1, v36
	v_fma_f32 v39, -v37, v36, v19
	v_fma_f32 v40, -v38, v36, v19
	v_cmp_ge_f32_e64 s[0:1], 0, v39
	s_nop 1
	v_cndmask_b32_e64 v36, v36, v37, s[0:1]
	v_cmp_lt_f32_e64 s[0:1], 0, v40
	s_nop 1
	v_cndmask_b32_e64 v36, v36, v38, s[0:1]
	v_mul_f32_e32 v37, 0x37800000, v36
	v_cndmask_b32_e32 v36, v36, v37, vcc
	v_cmp_class_f32_e32 vcc, v19, v206
	v_lshlrev_b32_e32 v38, 2, v85
	s_nop 0
	v_cndmask_b32_e32 v19, v36, v19, vcc
	v_div_scale_f32 v36, s[0:1], v19, v19, 1.0
	v_rcp_f32_e32 v37, v36
	v_div_scale_f32 v39, vcc, 1.0, v19, 1.0
	s_add_i32 s0, s78, 0x8000
	v_fma_f32 v40, -v36, v37, 1.0
	v_fmac_f32_e32 v37, v40, v37
	v_mul_f32_e32 v40, v39, v37
	v_fma_f32 v41, -v36, v40, v39
	v_fmac_f32_e32 v40, v41, v37
	v_fma_f32 v36, -v36, v40, v39
	v_div_fmas_f32 v36, v36, v37, v40
	v_div_fixup_f32 v36, v36, v19, 1.0
	v_pk_mul_f32 v[14:15], v[14:15], v[36:37] op_sel_hi:[1,0]
	v_pk_mul_f32 v[16:17], v[16:17], v[36:37] op_sel_hi:[1,0]
	s_waitcnt vmcnt(0)
	v_pk_fma_f32 v[14:15], v[30:31], v[14:15], v[46:47]
	v_pk_fma_f32 v[16:17], v[32:33], v[16:17], v[48:49]
	v_cvt_pk_bf16_f32 v14, v14, v15
	v_pk_mul_f32 v[10:11], v[10:11], v[36:37] op_sel_hi:[1,0]
	v_cvt_pk_bf16_f32 v15, v16, v17
	global_store_dwordx2 v[22:23], v[14:15], off
	global_load_dwordx4 v[14:17], v38, s[18:19] nt
	s_nop 0
	global_load_dwordx4 v[30:33], v[20:21], off offset:1024 nt
	global_load_dwordx4 v[42:45], v18, s[6:7] offset:1024 nt
	v_pk_mul_f32 v[12:13], v[12:13], v[36:37] op_sel_hi:[1,0]
	v_lshlrev_b32_e32 v19, 2, v87
	v_pk_mul_f32 v[6:7], v[6:7], v[36:37] op_sel_hi:[1,0]
	v_pk_mul_f32 v[8:9], v[8:9], v[36:37] op_sel_hi:[1,0]
	s_add_u32 s2, s2, s52
	v_pk_mul_f32 v[2:3], v[2:3], v[36:37] op_sel_hi:[1,0]
	s_addc_u32 s3, s3, s53
	v_pk_mul_f32 v[4:5], v[4:5], v[36:37] op_sel_hi:[1,0]
	s_cmp_lt_i32 s0, 0x8400
	s_waitcnt vmcnt(2)
	v_pk_add_f32 v[14:15], v[14:15], 1.0 op_sel_hi:[1,0]
	v_pk_add_f32 v[16:17], v[16:17], 1.0 op_sel_hi:[1,0]
	s_waitcnt vmcnt(1)
	v_pk_mul_f32 v[14:15], v[30:31], v[14:15]
	v_pk_mul_f32 v[16:17], v[32:33], v[16:17]
	s_waitcnt vmcnt(0)
	v_pk_fma_f32 v[10:11], v[14:15], v[10:11], v[42:43]
	v_pk_fma_f32 v[12:13], v[16:17], v[12:13], v[44:45]
	v_cvt_pk_bf16_f32 v10, v10, v11
	s_nop 0
	v_cvt_pk_bf16_f32 v11, v12, v13
	global_store_dwordx2 v[22:23], v[10:11], off offset:512
	global_load_dwordx4 v[10:13], v19, s[18:19] nt
	s_nop 0
	global_load_dwordx4 v[14:17], v[20:21], off offset:2048 nt
	global_load_dwordx4 v[30:33], v18, s[6:7] offset:2048 nt
	v_lshlrev_b32_e32 v19, 2, v88
	s_waitcnt vmcnt(2)
	v_pk_add_f32 v[10:11], v[10:11], 1.0 op_sel_hi:[1,0]
	v_pk_add_f32 v[12:13], v[12:13], 1.0 op_sel_hi:[1,0]
	s_waitcnt vmcnt(1)
	v_pk_mul_f32 v[10:11], v[14:15], v[10:11]
	v_pk_mul_f32 v[12:13], v[16:17], v[12:13]
	s_waitcnt vmcnt(0)
	v_pk_fma_f32 v[6:7], v[6:7], v[10:11], v[30:31]
	v_pk_fma_f32 v[8:9], v[8:9], v[12:13], v[32:33]
	v_cvt_pk_bf16_f32 v6, v6, v7
	s_nop 0
	v_cvt_pk_bf16_f32 v7, v8, v9
	global_store_dwordx2 v[22:23], v[6:7], off offset:1024
	global_load_dwordx4 v[6:9], v19, s[18:19] nt
	s_nop 0
	global_load_dwordx4 v[10:13], v[20:21], off offset:3072 nt
	global_load_dwordx4 v[14:17], v18, s[6:7] offset:3072 nt
	s_waitcnt vmcnt(2)
	v_pk_add_f32 v[6:7], v[6:7], 1.0 op_sel_hi:[1,0]
	v_pk_add_f32 v[8:9], v[8:9], 1.0 op_sel_hi:[1,0]
	s_waitcnt vmcnt(1)
	v_pk_mul_f32 v[6:7], v[10:11], v[6:7]
	v_pk_mul_f32 v[8:9], v[12:13], v[8:9]
	s_waitcnt vmcnt(0)
	v_pk_fma_f32 v[2:3], v[2:3], v[6:7], v[14:15]
	v_pk_fma_f32 v[4:5], v[4:5], v[8:9], v[16:17]
	v_cvt_pk_bf16_f32 v2, v2, v3
	s_nop 0
	v_cvt_pk_bf16_f32 v3, v4, v5
	global_store_dwordx2 v[22:23], v[2:3], off offset:1536
	v_lshl_add_u64 v[22:23], v[22:23], 0, s[66:67]
	s_cbranch_scc0 .LBB0_118
; template <int NR>
; __device__ __forceinline__ void norm_group(int m0, const float* src_lat, const float* src_ctx, bf16* H, const float* gain, const float* mod, int shoff, int scoff, int lane, const float* part, float* ctx_out) {
;     ...
;         for (int j = 0; j < 4; ++j) v[i][j] = *((const f32x4*)(xr + (size_t)i * D) + lane + 64 * j);
;     if (part && m0 >= MLAT) {
; #pragma unroll
;         for (int i = 0; i < NR; ++i)
; #pragma unroll
;             for (int j = 0; j < 4; ++j) { const size_t o = (size_t)(m0 - MLAT + i) * D + 4 * (lane + 64 * j);
;                 const f32x4 p0 = *(const f32x4*)(part + o), p1 = *(const f32x4*)(part + (size_t)MCTX * D + o), p2 = *(const f32x4*)(part + (size_t)2 * MCTX * D + o), p3 = *(const f32x4*)(part + (size_t)3 * MCTX * D + o);
;                 v[i][j] = v[i][j] + ((p0 + p1) + (p2 + p3)); *(f32x4*)(ctx_out + o) = v[i][j]; }
.LBB0_114:
	s_add_i32 s6, s78, 0x8000
	s_cmp_lt_i32 s6, 0x8000
	s_cselect_b32 s1, s3, 0
	s_cselect_b32 s0, s2, s78
	s_cselect_b32 s7, s75, s83
	s_cselect_b32 s18, s74, s82
	s_lshl_b64 s[0:1], s[0:1], 12
	s_add_u32 s0, s18, s0
	s_addc_u32 s1, s7, s1
	global_load_dwordx4 v[14:17], v34, s[0:1] nt
	global_load_dwordx4 v[10:13], v34, s[0:1] offset:1024 nt
	global_load_dwordx4 v[6:9], v34, s[0:1] offset:2048 nt
	global_load_dwordx4 v[2:5], v34, s[0:1] offset:3072 nt
	s_cmpk_gt_i32 s6, 0x7fff
	s_cselect_b64 s[0:1], -1, 0
	s_and_b64 s[18:19], s[8:9], s[0:1]
	s_mov_b64 s[0:1], -1
	s_and_b64 vcc, exec, s[18:19]
	s_cbranch_vccnz .LBB0_116
	s_mov_b64 s[0:1], 0
.LBB0_116:
	s_andn2_b64 vcc, exec, s[0:1]
	s_cbranch_vccnz .LBB0_113
	s_lshl_b64 s[0:1], s[78:79], 10
	v_mov_b32_e32 v31, s1
	v_or_b32_e32 v30, s0, v83
	v_lshlrev_b64 v[36:37], 2, v[30:31]
	v_lshl_add_u64 v[54:55], s[4:5], 0, v[36:37]
	v_lshl_add_u64 v[42:43], s[10:11], 0, v[36:37]
	v_lshl_add_u64 v[46:47], s[12:13], 0, v[36:37]
	v_lshl_add_u64 v[50:51], s[16:17], 0, v[36:37]
	global_load_dwordx4 v[30:33], v[54:55], off nt
	s_nop 0
	global_load_dwordx4 v[42:45], v[42:43], off nt
	s_nop 0
	global_load_dwordx4 v[46:49], v[46:47], off nt
	s_nop 0
	global_load_dwordx4 v[50:53], v[50:51], off nt
	v_mov_b32_e32 v57, s1
	v_or_b32_e32 v56, s0, v85
	v_lshl_add_u64 v[36:37], s[94:95], 0, v[36:37]
	v_lshlrev_b64 v[56:57], 2, v[56:57]
	v_lshl_add_u64 v[58:59], s[10:11], 0, v[56:57]
	v_lshl_add_u64 v[60:61], s[12:13], 0, v[56:57]
	v_lshl_add_u64 v[62:63], s[16:17], 0, v[56:57]
	v_lshl_add_u64 v[56:57], s[94:95], 0, v[56:57]
	s_waitcnt vmcnt(2)
	v_pk_add_f32 v[32:33], v[32:33], v[44:45]
	v_pk_add_f32 v[30:31], v[30:31], v[42:43]
	s_waitcnt vmcnt(0)
	v_pk_add_f32 v[42:43], v[48:49], v[52:53]
	v_pk_add_f32 v[44:45], v[46:47], v[50:51]
	v_pk_add_f32 v[32:33], v[32:33], v[42:43]
	v_pk_add_f32 v[30:31], v[30:31], v[44:45]
	v_pk_add_f32 v[16:17], v[16:17], v[32:33]
	v_pk_add_f32 v[14:15], v[14:15], v[30:31]
	global_store_dwordx4 v[36:37], v[14:17], off
	global_load_dwordx4 v[30:33], v[54:55], off offset:1024 nt
	global_load_dwordx4 v[42:45], v[58:59], off nt
	global_load_dwordx4 v[46:49], v[60:61], off nt
	global_load_dwordx4 v[50:53], v[62:63], off nt
	v_mov_b32_e32 v37, s1
	v_or_b32_e32 v36, s0, v87
	v_lshlrev_b64 v[36:37], 2, v[36:37]
	v_lshl_add_u64 v[58:59], s[10:11], 0, v[36:37]
	v_lshl_add_u64 v[60:61], s[12:13], 0, v[36:37]
	v_lshl_add_u64 v[62:63], s[16:17], 0, v[36:37]
	v_lshl_add_u64 v[36:37], s[94:95], 0, v[36:37]
	s_waitcnt vmcnt(2)
	v_pk_add_f32 v[32:33], v[32:33], v[44:45]
	v_pk_add_f32 v[30:31], v[30:31], v[42:43]
	s_waitcnt vmcnt(0)
	v_pk_add_f32 v[42:43], v[48:49], v[52:53]
	v_pk_add_f32 v[44:45], v[46:47], v[50:51]
	v_pk_add_f32 v[32:33], v[32:33], v[42:43]
	v_pk_add_f32 v[30:31], v[30:31], v[44:45]
	v_pk_add_f32 v[12:13], v[12:13], v[32:33]
	v_pk_add_f32 v[10:11], v[10:11], v[30:31]
	global_store_dwordx4 v[56:57], v[10:13], off
	global_load_dwordx4 v[30:33], v[54:55], off offset:2048 nt
	global_load_dwordx4 v[42:45], v[58:59], off nt
	global_load_dwordx4 v[46:49], v[60:61], off nt
	global_load_dwordx4 v[50:53], v[62:63], off nt
	v_mov_b32_e32 v57, s1
	v_or_b32_e32 v56, s0, v88
	v_lshlrev_b64 v[56:57], 2, v[56:57]
	v_lshl_add_u64 v[58:59], s[10:11], 0, v[56:57]
	v_lshl_add_u64 v[60:61], s[12:13], 0, v[56:57]
	v_lshl_add_u64 v[62:63], s[16:17], 0, v[56:57]
	s_waitcnt vmcnt(2)
	v_pk_add_f32 v[32:33], v[32:33], v[44:45]
	v_pk_add_f32 v[30:31], v[30:31], v[42:43]
	s_waitcnt vmcnt(0)
	v_pk_add_f32 v[42:43], v[48:49], v[52:53]
	v_pk_add_f32 v[44:45], v[46:47], v[50:51]
	v_pk_add_f32 v[32:33], v[32:33], v[42:43]
	v_pk_add_f32 v[30:31], v[30:31], v[44:45]
	v_pk_add_f32 v[8:9], v[8:9], v[32:33]
	v_pk_add_f32 v[6:7], v[6:7], v[30:31]
	global_store_dwordx4 v[36:37], v[6:9], off
	global_load_dwordx4 v[30:33], v[54:55], off offset:3072 nt
	global_load_dwordx4 v[42:45], v[58:59], off nt
	global_load_dwordx4 v[46:49], v[60:61], off nt
	global_load_dwordx4 v[50:53], v[62:63], off nt
	s_waitcnt vmcnt(2)
	v_pk_add_f32 v[32:33], v[32:33], v[44:45]
	v_pk_add_f32 v[30:31], v[30:31], v[42:43]
	s_waitcnt vmcnt(0)
	v_pk_add_f32 v[36:37], v[48:49], v[52:53]
	v_pk_add_f32 v[42:43], v[46:47], v[50:51]
	v_pk_add_f32 v[32:33], v[32:33], v[36:37]
	v_pk_add_f32 v[30:31], v[30:31], v[42:43]
	v_pk_add_f32 v[4:5], v[4:5], v[32:33]
	v_pk_add_f32 v[2:3], v[2:3], v[30:31]
	v_lshl_add_u64 v[30:31], s[94:95], 0, v[56:57]
	global_store_dwordx4 v[30:31], v[2:5], off
	s_branch .LBB0_113

; template <int NR>
; __device__ __forceinline__ void norm_group(int m0, const float* src_lat, const float* src_ctx, bf16* H, const float* gain, const float* mod, int shoff, int scoff, int lane, const float* part, float* ctx_out) {
;     const float* xr = (m0 < MLAT) ? src_lat + (size_t)m0 * D : src_ctx + (size_t)(m0 - MLAT) * D;
;     const int b = (m0 < MLAT) ? (m0 >> 13) : 4;
;     f32x4 v[NR][4]; float rstd[NR];
; #pragma unroll
;     for (int i = 0; i < NR; ++i)
; #pragma unroll
;         for (int j = 0; j < 4; ++j) v[i][j] = *((const f32x4*)(xr + (size_t)i * D) + lane + 64 * j);
;     if (part && m0 >= MLAT) {
; #pragma unroll
;         for (int i = 0; i < NR; ++i)
; #pragma unroll
;             for (int j = 0; j < 4; ++j) { const size_t o = (size_t)(m0 - MLAT + i) * D + 4 * (lane + 64 * j);
;                 const f32x4 p0 = *(const f32x4*)(part + o), p1 = *(const f32x4*)(part + (size_t)MCTX * D + o), p2 = *(const f32x4*)(part + (size_t)2 * MCTX * D + o), p3 = *(const f32x4*)(part + (size_t)3 * MCTX * D + o);
;                 v[i][j] = v[i][j] + ((p0 + p1) + (p2 + p3)); *(f32x4*)(ctx_out + o) = v[i][j]; }
;     }
; #pragma unroll
;     for (int i = 0; i < NR; ++i) { float s = 0.f;
; #pragma unroll
;         for (int j = 0; j < 4; ++j) s += (v[i][j].x * v[i][j].x + v[i][j].y * v[i][j].y) + (v[i][j].z * v[i][j].z + v[i][j].w * v[i][j].w);
;         rstd[i] = 1.0f / sqrtf(wave_sum(s) * (1.f / D) + EPS); }
.LBB0_615:
	s_ashr_i32 s9, s8, 31
	s_lshl_b64 s[0:1], s[8:9], 12
	v_lshl_add_u64 v[6:7], v[76:77], 0, s[0:1]
	global_load_dwordx4 v[70:73], v[6:7], off nt
	global_load_dwordx4 v[54:57], v[6:7], off offset:1024 nt
	global_load_dwordx4 v[30:33], v[6:7], off offset:2048 nt
	global_load_dwordx4 v[14:17], v[6:7], off offset:3072 nt
	v_add_co_u32_e32 v2, vcc, 0x1000, v6
	s_waitcnt vmcnt(3)
	v_pk_mul_f32 v[94:95], v[72:73], v[72:73]
	v_addc_co_u32_e32 v3, vcc, 0, v7, vcc
	global_load_dwordx4 v[66:69], v[2:3], off nt
	global_load_dwordx4 v[46:49], v[2:3], off offset:1024 nt
	global_load_dwordx4 v[18:21], v[2:3], off offset:2048 nt
	s_nop 0
	global_load_dwordx4 v[2:5], v[2:3], off offset:3072 nt
	v_pk_mul_f32 v[96:97], v[70:71], v[70:71]
	s_waitcnt vmcnt(4)
	v_mul_f32_e32 v38, v14, v14
	v_pk_mov_b32 v[98:99], v[96:97], v[94:95] op_sel:[1,0]
	v_mov_b32_e32 v97, v95
	v_pk_add_f32 v[94:95], v[98:99], v[96:97]
	v_pk_mul_f32 v[96:97], v[56:57], v[56:57]
	v_pk_mul_f32 v[98:99], v[54:55], v[54:55]
	v_mul_f32_e32 v39, v15, v15
	v_pk_mov_b32 v[100:101], v[98:99], v[96:97] op_sel:[1,0]
	v_mov_b32_e32 v99, v97
	v_pk_add_f32 v[96:97], v[100:101], v[98:99]
	v_pk_add_f32 v[94:95], v[94:95], v[94:95] op_sel:[0,1] op_sel_hi:[1,0]
	v_pk_add_f32 v[96:97], v[96:97], v[96:97] op_sel:[0,1] op_sel_hi:[1,0]
	v_mov_b32_e32 v95, v38
	v_mov_b32_e32 v97, v39
	v_mul_f32_e32 v80, v31, v31
	v_pk_add_f32 v[94:95], v[94:95], v[96:97]
	v_pk_fma_f32 v[96:97], v[30:31], v[30:31], v[80:81] op_sel_hi:[1,1,0]
	v_mul_f32_e32 v80, v33, v33
	v_mul_f32_e32 v40, v16, v16
	v_mul_f32_e32 v41, v17, v17
	v_pk_fma_f32 v[98:99], v[32:33], v[32:33], v[80:81] op_sel_hi:[1,1,0]
	v_mov_b32_e32 v97, v40
	v_mov_b32_e32 v99, v41
	v_pk_add_f32 v[96:97], v[96:97], v[98:99]
	v_add_co_u32_e32 v8, vcc, s96, v6
	v_pk_add_f32 v[94:95], v[94:95], v[96:97]
	s_nop 0
	v_addc_co_u32_e32 v9, vcc, 0, v7, vcc
	v_add_f32_e32 v38, v94, v95
	ds_bpermute_b32 v39, v37, v38
	v_add_co_u32_e32 v6, vcc, s87, v6
	s_waitcnt lgkmcnt(0)
	v_add_f32_e32 v38, v38, v39
	ds_bpermute_b32 v39, v89, v38
	v_addc_co_u32_e32 v7, vcc, 0, v7, vcc
	global_load_dwordx4 v[62:65], v[6:7], off offset:-4096 nt
	global_load_dwordx4 v[50:53], v[8:9], off offset:1024 nt
	global_load_dwordx4 v[26:29], v[8:9], off offset:2048 nt
	global_load_dwordx4 v[10:13], v[8:9], off offset:3072 nt
	global_load_dwordx4 v[58:61], v[6:7], off nt
	global_load_dwordx4 v[42:45], v[6:7], off offset:1024 nt
	global_load_dwordx4 v[22:25], v[6:7], off offset:2048 nt
	s_nop 0
	global_load_dwordx4 v[6:9], v[6:7], off offset:3072 nt
	s_waitcnt lgkmcnt(0)
	v_add_f32_e32 v38, v38, v39
	ds_bpermute_b32 v39, v90, v38
	s_waitcnt lgkmcnt(0)
	v_add_f32_e32 v38, v38, v39
	ds_bpermute_b32 v39, v91, v38
	s_waitcnt lgkmcnt(0)
	v_add_f32_e32 v38, v38, v39
	ds_bpermute_b32 v39, v92, v38
	s_waitcnt lgkmcnt(0)
	v_add_f32_e32 v38, v38, v39
	ds_bpermute_b32 v39, v93, v38
	s_waitcnt lgkmcnt(0)
	v_add_f32_e32 v38, v38, v39
	v_fmamk_f32 v38, v38, 0x3a800000, v205
	v_cmp_gt_f32_e32 vcc, s88, v38
	v_mul_f32_e32 v39, 0x4f800000, v38
	s_waitcnt vmcnt(11)
	v_pk_mul_f32 v[94:95], v[68:69], v[68:69]
	v_cndmask_b32_e32 v38, v38, v39, vcc
	v_sqrt_f32_e32 v39, v38
	v_pk_mul_f32 v[96:97], v[66:67], v[66:67]
	v_add_u32_e32 v40, -1, v39
	v_fma_f32 v41, -v40, v39, v38
	v_cmp_ge_f32_e64 s[0:1], 0, v41
	v_add_u32_e32 v41, 1, v39
	v_pk_mov_b32 v[98:99], v[96:97], v[94:95] op_sel:[1,0]
	v_cndmask_b32_e64 v40, v39, v40, s[0:1]
	v_fma_f32 v39, -v41, v39, v38
	v_cmp_lt_f32_e64 s[0:1], 0, v39
	v_mov_b32_e32 v97, v95
	v_pk_add_f32 v[94:95], v[98:99], v[96:97]
	v_cndmask_b32_e64 v39, v40, v41, s[0:1]
	v_mul_f32_e32 v40, 0x37800000, v39
	v_cndmask_b32_e32 v39, v39, v40, vcc
	v_cmp_class_f32_e32 vcc, v38, v206
	s_waitcnt vmcnt(10)
	v_pk_mul_f32 v[96:97], v[48:49], v[48:49]
	v_pk_mul_f32 v[98:99], v[46:47], v[46:47]
	v_cndmask_b32_e32 v38, v39, v38, vcc
	v_div_scale_f32 v39, s[0:1], v38, v38, 1.0
	v_rcp_f32_e32 v40, v39
	v_pk_mov_b32 v[100:101], v[98:99], v[96:97] op_sel:[1,0]
	v_mov_b32_e32 v99, v97
	v_pk_add_f32 v[96:97], v[100:101], v[98:99]
	v_fma_f32 v41, -v39, v40, 1.0
	v_fmac_f32_e32 v40, v41, v40
	v_div_scale_f32 v41, vcc, 1.0, v38, 1.0
	v_mul_f32_e32 v80, v41, v40
	v_fma_f32 v82, -v39, v80, v41
	v_fmac_f32_e32 v80, v82, v40
	v_fma_f32 v39, -v39, v80, v41
	v_div_fmas_f32 v39, v39, v40, v80
	v_div_fixup_f32 v80, v39, v38, 1.0
	s_waitcnt vmcnt(8)
	v_mul_f32_e32 v38, v2, v2
	v_mul_f32_e32 v39, v3, v3
	v_pk_add_f32 v[94:95], v[94:95], v[94:95] op_sel:[0,1] op_sel_hi:[1,0]
	v_pk_add_f32 v[96:97], v[96:97], v[96:97] op_sel:[0,1] op_sel_hi:[1,0]
	v_mov_b32_e32 v95, v38
	v_mov_b32_e32 v97, v39
	v_mul_f32_e32 v82, v19, v19
	v_pk_add_f32 v[94:95], v[94:95], v[96:97]
	v_pk_fma_f32 v[96:97], v[18:19], v[18:19], v[82:83] op_sel_hi:[1,1,0]
	v_mul_f32_e32 v82, v21, v21
	v_mul_f32_e32 v40, v4, v4
	v_mul_f32_e32 v41, v5, v5
	v_pk_fma_f32 v[98:99], v[20:21], v[20:21], v[82:83] op_sel_hi:[1,1,0]
	v_mov_b32_e32 v97, v40
	v_mov_b32_e32 v99, v41
	v_pk_add_f32 v[96:97], v[96:97], v[98:99]
	v_pk_mul_f32 v[70:71], v[70:71], v[80:81] op_sel_hi:[1,0]
	v_pk_add_f32 v[94:95], v[94:95], v[96:97]
	s_waitcnt vmcnt(7)
	v_pk_mul_f32 v[96:97], v[62:63], v[62:63]
	v_add_f32_e32 v38, v94, v95
	ds_bpermute_b32 v39, v37, v38
	v_pk_mul_f32 v[94:95], v[64:65], v[64:65]
	v_pk_mul_f32 v[72:73], v[72:73], v[80:81] op_sel_hi:[1,0]
	v_pk_mov_b32 v[98:99], v[96:97], v[94:95] op_sel:[1,0]
	v_mov_b32_e32 v97, v95
	s_waitcnt lgkmcnt(0)
	v_add_f32_e32 v38, v38, v39
	ds_bpermute_b32 v39, v89, v38
	v_pk_add_f32 v[94:95], v[98:99], v[96:97]
	s_waitcnt vmcnt(6)
	v_pk_mul_f32 v[96:97], v[52:53], v[52:53]
	v_pk_mul_f32 v[98:99], v[50:51], v[50:51]
	v_pk_add_f32 v[94:95], v[94:95], v[94:95] op_sel:[0,1] op_sel_hi:[1,0]
	s_waitcnt lgkmcnt(0)
; template <int NR>
; __device__ __forceinline__ void norm_group(int m0, const float* src_lat, const float* src_ctx, bf16* H, const float* gain, const float* mod, int shoff, int scoff, int lane, const float* part, float* ctx_out) {
;     ...
; #pragma unroll
;     for (int i = 0; i < NR; ++i) { float s = 0.f;
; #pragma unroll
;         for (int j = 0; j < 4; ++j) s += (v[i][j].x * v[i][j].x + v[i][j].y * v[i][j].y) + (v[i][j].z * v[i][j].z + v[i][j].w * v[i][j].w);
;         rstd[i] = 1.0f / sqrtf(wave_sum(s) * (1.f / D) + EPS); }
	v_add_f32_e32 v38, v38, v39
	ds_bpermute_b32 v39, v90, v38
	v_pk_mov_b32 v[100:101], v[98:99], v[96:97] op_sel:[1,0]
	v_mov_b32_e32 v99, v97
	v_pk_add_f32 v[96:97], v[100:101], v[98:99]
	v_pk_mul_f32 v[54:55], v[54:55], v[80:81] op_sel_hi:[1,0]
	s_waitcnt lgkmcnt(0)
	v_add_f32_e32 v38, v38, v39
	ds_bpermute_b32 v39, v91, v38
	v_pk_add_f32 v[96:97], v[96:97], v[96:97] op_sel:[0,1] op_sel_hi:[1,0]
	v_pk_mul_f32 v[56:57], v[56:57], v[80:81] op_sel_hi:[1,0]
	v_pk_mul_f32 v[30:31], v[30:31], v[80:81] op_sel_hi:[1,0]
	v_pk_mul_f32 v[32:33], v[32:33], v[80:81] op_sel_hi:[1,0]
	s_waitcnt lgkmcnt(0)
	v_add_f32_e32 v38, v38, v39
	ds_bpermute_b32 v39, v92, v38
	v_pk_mul_f32 v[14:15], v[14:15], v[80:81] op_sel_hi:[1,0]
	v_pk_mul_f32 v[16:17], v[16:17], v[80:81] op_sel_hi:[1,0]
	s_waitcnt lgkmcnt(0)
	v_add_f32_e32 v38, v38, v39
	ds_bpermute_b32 v39, v93, v38
	s_waitcnt lgkmcnt(0)
	v_add_f32_e32 v38, v38, v39
	v_fmamk_f32 v38, v38, 0x3a800000, v205
	v_cmp_gt_f32_e32 vcc, s88, v38
	v_mul_f32_e32 v39, 0x4f800000, v38
	s_nop 0
	v_cndmask_b32_e32 v38, v38, v39, vcc
	v_sqrt_f32_e32 v39, v38
	s_nop 0
	v_add_u32_e32 v40, -1, v39
	v_fma_f32 v41, -v40, v39, v38
	v_cmp_ge_f32_e64 s[0:1], 0, v41
	v_add_u32_e32 v41, 1, v39
	s_nop 0
	v_cndmask_b32_e64 v40, v39, v40, s[0:1]
	v_fma_f32 v39, -v41, v39, v38
	v_cmp_lt_f32_e64 s[0:1], 0, v39
	s_nop 1
	v_cndmask_b32_e64 v39, v40, v41, s[0:1]
	v_mul_f32_e32 v40, 0x37800000, v39
	v_cndmask_b32_e32 v39, v39, v40, vcc
	v_cmp_class_f32_e32 vcc, v38, v206
	s_nop 1
	v_cndmask_b32_e32 v38, v39, v38, vcc
	v_div_scale_f32 v39, s[0:1], v38, v38, 1.0
	v_rcp_f32_e32 v40, v39
	s_nop 0
	v_fma_f32 v41, -v39, v40, 1.0
	v_fmac_f32_e32 v40, v41, v40
	v_div_scale_f32 v41, vcc, 1.0, v38, 1.0
	v_mul_f32_e32 v82, v41, v40
	v_fma_f32 v84, -v39, v82, v41
	v_fmac_f32_e32 v82, v84, v40
	v_fma_f32 v39, -v39, v82, v41
	v_div_fmas_f32 v39, v39, v40, v82
	v_div_fixup_f32 v82, v39, v38, 1.0
	s_waitcnt vmcnt(4)
	v_mul_f32_e32 v38, v10, v10
	v_mul_f32_e32 v39, v11, v11
	v_mov_b32_e32 v95, v38
	v_mov_b32_e32 v97, v39
	v_mul_f32_e32 v84, v27, v27
	v_pk_add_f32 v[94:95], v[94:95], v[96:97]
	v_pk_fma_f32 v[96:97], v[26:27], v[26:27], v[84:85] op_sel_hi:[1,1,0]
	v_mul_f32_e32 v84, v29, v29
	v_mul_f32_e32 v40, v12, v12
	v_mul_f32_e32 v41, v13, v13
	v_pk_fma_f32 v[98:99], v[28:29], v[28:29], v[84:85] op_sel_hi:[1,1,0]
	v_mov_b32_e32 v97, v40
	v_mov_b32_e32 v99, v41
	v_pk_add_f32 v[96:97], v[96:97], v[98:99]
	v_pk_mul_f32 v[66:67], v[66:67], v[82:83] op_sel_hi:[1,0]
	v_pk_add_f32 v[94:95], v[94:95], v[96:97]
	s_waitcnt vmcnt(3)
	v_pk_mul_f32 v[96:97], v[58:59], v[58:59]
	v_add_f32_e32 v38, v94, v95
	ds_bpermute_b32 v39, v37, v38
	v_pk_mul_f32 v[94:95], v[60:61], v[60:61]
	v_pk_mul_f32 v[68:69], v[68:69], v[82:83] op_sel_hi:[1,0]
	v_pk_mov_b32 v[98:99], v[96:97], v[94:95] op_sel:[1,0]
	v_mov_b32_e32 v97, v95
	s_waitcnt lgkmcnt(0)
	v_add_f32_e32 v38, v38, v39
	ds_bpermute_b32 v39, v89, v38
	v_pk_add_f32 v[94:95], v[98:99], v[96:97]
	s_waitcnt vmcnt(2)
	v_pk_mul_f32 v[96:97], v[44:45], v[44:45]
	v_pk_mul_f32 v[98:99], v[42:43], v[42:43]
	v_pk_add_f32 v[94:95], v[94:95], v[94:95] op_sel:[0,1] op_sel_hi:[1,0]
	s_waitcnt lgkmcnt(0)
	v_add_f32_e32 v38, v38, v39
	ds_bpermute_b32 v39, v90, v38
	v_pk_mov_b32 v[100:101], v[98:99], v[96:97] op_sel:[1,0]
	v_mov_b32_e32 v99, v97
	v_pk_add_f32 v[96:97], v[100:101], v[98:99]
	v_pk_mul_f32 v[46:47], v[46:47], v[82:83] op_sel_hi:[1,0]
	s_waitcnt lgkmcnt(0)
	v_add_f32_e32 v38, v38, v39
	ds_bpermute_b32 v39, v91, v38
	v_pk_add_f32 v[96:97], v[96:97], v[96:97] op_sel:[0,1] op_sel_hi:[1,0]
	v_pk_mul_f32 v[48:49], v[48:49], v[82:83] op_sel_hi:[1,0]
	v_pk_mul_f32 v[18:19], v[18:19], v[82:83] op_sel_hi:[1,0]
	v_pk_mul_f32 v[20:21], v[20:21], v[82:83] op_sel_hi:[1,0]
	s_waitcnt lgkmcnt(0)
	v_add_f32_e32 v38, v38, v39
	ds_bpermute_b32 v39, v92, v38
	v_pk_mul_f32 v[2:3], v[2:3], v[82:83] op_sel_hi:[1,0]
	v_pk_mul_f32 v[4:5], v[4:5], v[82:83] op_sel_hi:[1,0]
	s_waitcnt lgkmcnt(0)
	v_add_f32_e32 v38, v38, v39
	ds_bpermute_b32 v39, v93, v38
	s_waitcnt lgkmcnt(0)
	v_add_f32_e32 v38, v38, v39
	v_fmamk_f32 v38, v38, 0x3a800000, v205
	v_cmp_gt_f32_e32 vcc, s88, v38
	v_mul_f32_e32 v39, 0x4f800000, v38
	s_nop 0
	v_cndmask_b32_e32 v38, v38, v39, vcc
	v_sqrt_f32_e32 v39, v38
	s_nop 0
	v_add_u32_e32 v40, -1, v39
	v_fma_f32 v41, -v40, v39, v38
	v_cmp_ge_f32_e64 s[0:1], 0, v41
	v_add_u32_e32 v41, 1, v39
	s_nop 0
	v_cndmask_b32_e64 v40, v39, v40, s[0:1]
	v_fma_f32 v39, -v41, v39, v38
	v_cmp_lt_f32_e64 s[0:1], 0, v39
	s_nop 1
	v_cndmask_b32_e64 v39, v40, v41, s[0:1]
	v_mul_f32_e32 v40, 0x37800000, v39
	v_cndmask_b32_e32 v39, v39, v40, vcc
	v_cmp_class_f32_e32 vcc, v38, v206
	s_nop 1
	v_cndmask_b32_e32 v38, v39, v38, vcc
	v_div_scale_f32 v39, s[0:1], v38, v38, 1.0
	v_rcp_f32_e32 v40, v39
	s_nop 0
	v_fma_f32 v41, -v39, v40, 1.0
	v_fmac_f32_e32 v40, v41, v40
	v_div_scale_f32 v41, vcc, 1.0, v38, 1.0
	v_mul_f32_e32 v84, v41, v40
	v_fma_f32 v86, -v39, v84, v41
	v_fmac_f32_e32 v84, v86, v40
	v_fma_f32 v39, -v39, v84, v41
	v_div_fmas_f32 v39, v39, v40, v84
	v_div_fixup_f32 v84, v39, v38, 1.0
	s_waitcnt vmcnt(0)
	v_mul_f32_e32 v38, v6, v6
	v_mul_f32_e32 v39, v7, v7
	v_mov_b32_e32 v95, v38
	v_mov_b32_e32 v97, v39
	v_mul_f32_e32 v86, v23, v23
	v_pk_add_f32 v[94:95], v[94:95], v[96:97]
	v_pk_fma_f32 v[96:97], v[22:23], v[22:23], v[86:87] op_sel_hi:[1,1,0]
	v_mul_f32_e32 v86, v25, v25
	v_mul_f32_e32 v40, v8, v8
	v_mul_f32_e32 v41, v9, v9
	v_pk_fma_f32 v[98:99], v[24:25], v[24:25], v[86:87] op_sel_hi:[1,1,0]
	v_mov_b32_e32 v97, v40
	v_mov_b32_e32 v99, v41
	v_pk_add_f32 v[96:97], v[96:97], v[98:99]
	v_pk_mul_f32 v[62:63], v[62:63], v[84:85] op_sel_hi:[1,0]
	v_pk_add_f32 v[94:95], v[94:95], v[96:97]
	v_pk_mul_f32 v[64:65], v[64:65], v[84:85] op_sel_hi:[1,0]
	v_add_f32_e32 v38, v94, v95
	ds_bpermute_b32 v39, v37, v38
	s_waitcnt lgkmcnt(0)
; __device__ __forceinline__ unsigned pk2(float lo, float hi) { return cvtpk(lo, hi); }
; template <int NR>
; __device__ __forceinline__ void norm_group(int m0, const float* src_lat, const float* src_ctx, bf16* H, const float* gain, const float* mod, int shoff, int scoff, int lane, const float* part, float* ctx_out) {
;     ...
; #pragma unroll
;     for (int i = 0; i < NR; ++i) { float s = 0.f;
; #pragma unroll
;         for (int j = 0; j < 4; ++j) s += (v[i][j].x * v[i][j].x + v[i][j].y * v[i][j].y) + (v[i][j].z * v[i][j].z + v[i][j].w * v[i][j].w);
;         rstd[i] = 1.0f / sqrtf(wave_sum(s) * (1.f / D) + EPS); }
;     const float* mr = mod + b * 6144;
; #pragma unroll
;     for (int j = 0; j < 4; ++j) { const int idx = 4 * (lane + 64 * j);
;         const f32x4 g = *(const f32x4*)(gain + idx), sc = *(const f32x4*)(mr + scoff + idx), sh = *(const f32x4*)(mr + shoff + idx);
;         const f32x4 gs = g * (1.f + sc);
; #pragma unroll
;         for (int i = 0; i < NR; ++i) { const f32x4 y = v[i][j] * rstd[i] * gs + sh;
;             v2u o; o.x = pk2(y.x, y.y); o.y = pk2(y.z, y.w);
;             *(v2u*)(H + (size_t)(m0 + i) * D + idx) = o; } }
	v_add_f32_e32 v38, v38, v39
	ds_bpermute_b32 v39, v89, v38
	s_waitcnt lgkmcnt(0)
	v_add_f32_e32 v38, v38, v39
	ds_bpermute_b32 v39, v90, v38
	s_waitcnt lgkmcnt(0)
	v_add_f32_e32 v38, v38, v39
	ds_bpermute_b32 v39, v91, v38
	s_waitcnt lgkmcnt(0)
	v_add_f32_e32 v38, v38, v39
	ds_bpermute_b32 v39, v92, v38
	s_waitcnt lgkmcnt(0)
	v_add_f32_e32 v38, v38, v39
	ds_bpermute_b32 v39, v93, v38
	s_waitcnt lgkmcnt(0)
	v_add_f32_e32 v38, v38, v39
	v_fmamk_f32 v38, v38, 0x3a800000, v205
	v_cmp_gt_f32_e32 vcc, s88, v38
	v_mul_f32_e32 v39, 0x4f800000, v38
	s_nop 0
	v_cndmask_b32_e32 v38, v38, v39, vcc
	v_sqrt_f32_e32 v39, v38
	s_nop 0
	v_add_u32_e32 v40, -1, v39
	v_fma_f32 v41, -v40, v39, v38
	v_cmp_ge_f32_e64 s[0:1], 0, v41
	v_add_u32_e32 v41, 1, v39
	s_nop 0
	v_cndmask_b32_e64 v40, v39, v40, s[0:1]
	v_fma_f32 v39, -v41, v39, v38
	v_cmp_lt_f32_e64 s[0:1], 0, v39
	s_nop 1
	v_cndmask_b32_e64 v39, v40, v41, s[0:1]
	v_mul_f32_e32 v40, 0x37800000, v39
	v_cndmask_b32_e32 v39, v39, v40, vcc
	v_cmp_class_f32_e32 vcc, v38, v206
	s_nop 1
	v_cndmask_b32_e32 v38, v39, v38, vcc
	v_div_scale_f32 v39, s[0:1], v38, v38, 1.0
	s_lshr_b32 s0, s18, 11
	v_rcp_f32_e32 v40, v39
	s_mulk_i32 s0, 0x1800
	s_ashr_i32 s1, s0, 31
	s_lshl_b64 s[0:1], s[0:1], 2
	s_add_u32 s0, s72, s0
	v_fma_f32 v41, -v39, v40, 1.0
	s_addc_u32 s1, s74, s1
	v_fmac_f32_e32 v40, v41, v40
	v_div_scale_f32 v41, vcc, 1.0, v38, 1.0
	s_add_u32 s2, s0, 0x4000
	v_mul_f32_e32 v86, v41, v40
	s_addc_u32 s3, s1, 0
	v_fma_f32 v94, -v39, v86, v41
	s_add_u32 s0, s0, 0x3000
	v_fmac_f32_e32 v86, v94, v40
	s_addc_u32 s1, s1, 0
	global_load_dwordx4 v[94:97], v[78:79], off nt
	global_load_dwordx4 v[98:101], v34, s[2:3] nt
	global_load_dwordx4 v[102:105], v34, s[0:1] nt
	v_fma_f32 v39, -v39, v86, v41
	v_div_fmas_f32 v39, v39, v40, v86
	v_div_fixup_f32 v86, v39, v38, 1.0
	s_add_i32 s10, s8, 1
	s_add_i32 s12, s8, 2
	s_add_i32 s14, s8, 3
	s_ashr_i32 s11, s10, 31
	s_ashr_i32 s13, s12, 31
	v_pk_mul_f32 v[58:59], v[58:59], v[86:87] op_sel_hi:[1,0]
	v_pk_mul_f32 v[60:61], v[60:61], v[86:87] op_sel_hi:[1,0]
	s_ashr_i32 s15, s14, 31
	s_lshl_b64 s[16:17], s[8:9], 11
	s_lshl_b64 s[10:11], s[10:11], 11
	s_lshl_b64 s[12:13], s[12:13], 11
	s_lshl_b64 s[14:15], s[14:15], 11
	v_lshlrev_b32_e32 v38, 1, v83
	v_pk_mul_f32 v[42:43], v[42:43], v[86:87] op_sel_hi:[1,0]
	v_pk_mul_f32 v[44:45], v[44:45], v[86:87] op_sel_hi:[1,0]
	s_waitcnt vmcnt(1)
	v_pk_add_f32 v[100:101], v[100:101], 1.0 op_sel_hi:[1,0]
	v_pk_add_f32 v[98:99], v[98:99], 1.0 op_sel_hi:[1,0]
	v_pk_mul_f32 v[96:97], v[96:97], v[100:101]
	v_pk_mul_f32 v[94:95], v[94:95], v[98:99]
	s_waitcnt vmcnt(0)
	v_pk_fma_f32 v[72:73], v[72:73], v[96:97], v[104:105]
	v_pk_fma_f32 v[70:71], v[70:71], v[94:95], v[102:103]
	v_pk_fma_f32 v[68:69], v[68:69], v[96:97], v[104:105]
	v_pk_fma_f32 v[66:67], v[66:67], v[94:95], v[102:103]
	v_pk_fma_f32 v[64:65], v[64:65], v[96:97], v[104:105]
	v_pk_fma_f32 v[62:63], v[62:63], v[94:95], v[102:103]
	v_pk_fma_f32 v[60:61], v[96:97], v[60:61], v[104:105]
	v_pk_fma_f32 v[58:59], v[94:95], v[58:59], v[102:103]
	v_cvt_pk_bf16_f32 v70, v70, v71
	v_cvt_pk_bf16_f32 v71, v72, v73
	v_lshl_add_u64 v[72:73], v[74:75], 0, s[16:17]
	v_cvt_pk_bf16_f32 v66, v66, v67
	v_cvt_pk_bf16_f32 v67, v68, v69
	v_lshl_add_u64 v[68:69], v[74:75], 0, s[10:11]
	v_cvt_pk_bf16_f32 v62, v62, v63
	v_cvt_pk_bf16_f32 v63, v64, v65
	v_lshl_add_u64 v[64:65], v[74:75], 0, s[12:13]
	v_cvt_pk_bf16_f32 v58, v58, v59
	v_cvt_pk_bf16_f32 v59, v60, v61
	v_lshl_add_u64 v[60:61], v[74:75], 0, s[14:15]
	global_store_dwordx2 v[72:73], v[70:71], off
	global_store_dwordx2 v[68:69], v[66:67], off
	global_store_dwordx2 v[64:65], v[62:63], off
	global_store_dwordx2 v[60:61], v[58:59], off
	v_lshlrev_b32_e32 v62, 2, v83
	global_load_dwordx4 v[58:61], v[78:79], off offset:1024 nt
	global_load_dwordx4 v[64:67], v62, s[2:3] nt
	global_load_dwordx4 v[68:71], v62, s[0:1] nt
	s_add_u32 s16, s90, s16
	s_addc_u32 s17, s91, s17
	s_add_u32 s10, s90, s10
	s_addc_u32 s11, s91, s11
	s_add_u32 s12, s90, s12
	s_addc_u32 s13, s91, s13
	s_add_u32 s14, s90, s14
	s_addc_u32 s15, s91, s15
	s_add_i32 s18, s18, s52
	s_add_i32 s8, s8, s59
	s_cmpk_gt_i32 s18, 0x1fff
	s_waitcnt vmcnt(1)
; __device__ __forceinline__ unsigned pk2(float lo, float hi) { return cvtpk(lo, hi); }
; template <int NR>
; __device__ __forceinline__ void norm_group(int m0, const float* src_lat, const float* src_ctx, bf16* H, const float* gain, const float* mod, int shoff, int scoff, int lane, const float* part, float* ctx_out) {
;     ...
;     const float* mr = mod + b * 6144;
; #pragma unroll
;     for (int j = 0; j < 4; ++j) { const int idx = 4 * (lane + 64 * j);
;         const f32x4 g = *(const f32x4*)(gain + idx), sc = *(const f32x4*)(mr + scoff + idx), sh = *(const f32x4*)(mr + shoff + idx);
;         const f32x4 gs = g * (1.f + sc);
; #pragma unroll
;         for (int i = 0; i < NR; ++i) { const f32x4 y = v[i][j] * rstd[i] * gs + sh;
;             v2u o; o.x = pk2(y.x, y.y); o.y = pk2(y.z, y.w);
;             *(v2u*)(H + (size_t)(m0 + i) * D + idx) = o; } }
	v_pk_add_f32 v[64:65], v[64:65], 1.0 op_sel_hi:[1,0]
	v_pk_add_f32 v[62:63], v[66:67], 1.0 op_sel_hi:[1,0]
	v_pk_mul_f32 v[58:59], v[58:59], v[64:65]
	v_pk_mul_f32 v[60:61], v[60:61], v[62:63]
	s_waitcnt vmcnt(0)
	v_pk_fma_f32 v[46:47], v[46:47], v[58:59], v[68:69]
	v_pk_fma_f32 v[48:49], v[48:49], v[60:61], v[70:71]
	v_cvt_pk_bf16_f32 v46, v46, v47
	v_pk_fma_f32 v[54:55], v[54:55], v[58:59], v[68:69]
	v_cvt_pk_bf16_f32 v47, v48, v49
	global_store_dwordx2 v38, v[46:47], s[10:11]
	v_pk_mul_f32 v[46:47], v[50:51], v[84:85] op_sel_hi:[1,0]
	v_pk_mul_f32 v[48:49], v[52:53], v[84:85] op_sel_hi:[1,0]
	v_pk_fma_f32 v[46:47], v[46:47], v[58:59], v[68:69]
	v_pk_fma_f32 v[42:43], v[42:43], v[58:59], v[68:69]
	v_pk_fma_f32 v[56:57], v[56:57], v[60:61], v[70:71]
	v_cvt_pk_bf16_f32 v54, v54, v55
	v_pk_fma_f32 v[48:49], v[48:49], v[60:61], v[70:71]
	v_cvt_pk_bf16_f32 v55, v56, v57
	global_store_dwordx2 v38, v[54:55], s[16:17]
	v_cvt_pk_bf16_f32 v46, v46, v47
	v_cvt_pk_bf16_f32 v47, v48, v49
	global_store_dwordx2 v38, v[46:47], s[12:13]
	v_pk_fma_f32 v[44:45], v[44:45], v[60:61], v[70:71]
	v_cvt_pk_bf16_f32 v42, v42, v43
	s_nop 0
	v_cvt_pk_bf16_f32 v43, v44, v45
	global_store_dwordx2 v38, v[42:43], s[14:15]
	v_lshlrev_b32_e32 v38, 2, v85
	global_load_dwordx4 v[42:45], v[78:79], off offset:2048 nt
	global_load_dwordx4 v[46:49], v38, s[2:3] nt
	global_load_dwordx4 v[50:53], v38, s[0:1] nt
	s_waitcnt vmcnt(1)
	v_pk_add_f32 v[48:49], v[48:49], 1.0 op_sel_hi:[1,0]
	v_pk_add_f32 v[46:47], v[46:47], 1.0 op_sel_hi:[1,0]
	v_pk_mul_f32 v[44:45], v[44:45], v[48:49]
	v_pk_mul_f32 v[42:43], v[42:43], v[46:47]
	s_waitcnt vmcnt(0)
	v_pk_fma_f32 v[32:33], v[32:33], v[44:45], v[52:53]
	v_pk_fma_f32 v[30:31], v[30:31], v[42:43], v[50:51]
	v_pk_fma_f32 v[18:19], v[18:19], v[42:43], v[50:51]
	v_cvt_pk_bf16_f32 v30, v30, v31
	v_cvt_pk_bf16_f32 v31, v32, v33
	v_lshlrev_b32_e32 v32, 1, v85
	v_pk_fma_f32 v[20:21], v[20:21], v[44:45], v[52:53]
	v_cvt_pk_bf16_f32 v18, v18, v19
	global_store_dwordx2 v32, v[30:31], s[16:17]
	v_cvt_pk_bf16_f32 v19, v20, v21
	global_store_dwordx2 v32, v[18:19], s[10:11]
	v_pk_mul_f32 v[18:19], v[26:27], v[84:85] op_sel_hi:[1,0]
	v_pk_mul_f32 v[20:21], v[28:29], v[84:85] op_sel_hi:[1,0]
	v_pk_fma_f32 v[18:19], v[18:19], v[42:43], v[50:51]
	v_pk_fma_f32 v[20:21], v[20:21], v[44:45], v[52:53]
	v_cvt_pk_bf16_f32 v18, v18, v19
	v_lshlrev_b32_e32 v26, 2, v87
	v_cvt_pk_bf16_f32 v19, v20, v21
	global_store_dwordx2 v32, v[18:19], s[12:13]
	v_pk_mul_f32 v[18:19], v[22:23], v[86:87] op_sel_hi:[1,0]
	v_pk_mul_f32 v[20:21], v[24:25], v[86:87] op_sel_hi:[1,0]
	v_pk_fma_f32 v[18:19], v[18:19], v[42:43], v[50:51]
	v_pk_fma_f32 v[20:21], v[20:21], v[44:45], v[52:53]
	v_cvt_pk_bf16_f32 v18, v18, v19
	s_nop 0
	v_cvt_pk_bf16_f32 v19, v20, v21
	global_store_dwordx2 v32, v[18:19], s[14:15]
	global_load_dwordx4 v[18:21], v[78:79], off offset:3072 nt
	s_nop 0
	global_load_dwordx4 v[22:25], v26, s[2:3] nt
	s_nop 0
	global_load_dwordx4 v[26:29], v26, s[0:1] nt
	s_waitcnt vmcnt(1)
	v_pk_add_f32 v[24:25], v[24:25], 1.0 op_sel_hi:[1,0]
	v_pk_add_f32 v[22:23], v[22:23], 1.0 op_sel_hi:[1,0]
	v_pk_mul_f32 v[20:21], v[20:21], v[24:25]
	v_pk_mul_f32 v[18:19], v[18:19], v[22:23]
	s_waitcnt vmcnt(0)
	v_pk_fma_f32 v[16:17], v[16:17], v[20:21], v[28:29]
	v_pk_fma_f32 v[14:15], v[14:15], v[18:19], v[26:27]
	v_pk_fma_f32 v[2:3], v[2:3], v[18:19], v[26:27]
	v_cvt_pk_bf16_f32 v14, v14, v15
	v_cvt_pk_bf16_f32 v15, v16, v17
	v_lshlrev_b32_e32 v16, 1, v87
	v_pk_fma_f32 v[4:5], v[4:5], v[20:21], v[28:29]
	v_cvt_pk_bf16_f32 v2, v2, v3
	global_store_dwordx2 v16, v[14:15], s[16:17]
	v_cvt_pk_bf16_f32 v3, v4, v5
	global_store_dwordx2 v16, v[2:3], s[10:11]
	v_pk_mul_f32 v[2:3], v[10:11], v[84:85] op_sel_hi:[1,0]
	v_pk_mul_f32 v[4:5], v[12:13], v[84:85] op_sel_hi:[1,0]
	v_pk_fma_f32 v[2:3], v[2:3], v[18:19], v[26:27]
	v_pk_fma_f32 v[4:5], v[4:5], v[20:21], v[28:29]
	v_cvt_pk_bf16_f32 v2, v2, v3
	s_nop 0
	v_cvt_pk_bf16_f32 v3, v4, v5
	global_store_dwordx2 v16, v[2:3], s[12:13]
	v_pk_mul_f32 v[2:3], v[6:7], v[86:87] op_sel_hi:[1,0]
	v_pk_mul_f32 v[4:5], v[8:9], v[86:87] op_sel_hi:[1,0]
	v_pk_fma_f32 v[2:3], v[2:3], v[18:19], v[26:27]
	v_pk_fma_f32 v[4:5], v[4:5], v[20:21], v[28:29]
	v_cvt_pk_bf16_f32 v2, v2, v3
	s_nop 0
	v_cvt_pk_bf16_f32 v3, v4, v5
	global_store_dwordx2 v16, v[2:3], s[14:15]
	s_cbranch_scc0 .LBB0_615

; __device__ __forceinline__ unsigned pk2(float lo, float hi) { return cvtpk(lo, hi); }
; template <int NR>
; __device__ __forceinline__ void norm_group(int m0, const float* src_lat, const float* src_ctx, bf16* H, const float* gain, const float* mod, int shoff, int scoff, int lane, const float* part, float* ctx_out) {
;     ...
; #pragma unroll
;     for (int i = 0; i < NR; ++i) { float s = 0.f;
; #pragma unroll
;         for (int j = 0; j < 4; ++j) s += (v[i][j].x * v[i][j].x + v[i][j].y * v[i][j].y) + (v[i][j].z * v[i][j].z + v[i][j].w * v[i][j].w);
;         rstd[i] = 1.0f / sqrtf(wave_sum(s) * (1.f / D) + EPS); }
;     const float* mr = mod + b * 6144;
; #pragma unroll
;     for (int j = 0; j < 4; ++j) { const int idx = 4 * (lane + 64 * j);
;         const f32x4 g = *(const f32x4*)(gain + idx), sc = *(const f32x4*)(mr + scoff + idx), sh = *(const f32x4*)(mr + shoff + idx);
;         const f32x4 gs = g * (1.f + sc);
; #pragma unroll
;         for (int i = 0; i < NR; ++i) { const f32x4 y = v[i][j] * rstd[i] * gs + sh;
;             v2u o; o.x = pk2(y.x, y.y); o.y = pk2(y.z, y.w);
;             *(v2u*)(H + (size_t)(m0 + i) * D + idx) = o; } }
; __device__ __forceinline__ void norm_pass(const float* src_lat, const float* src_ctx, bf16* H, const float* gain, const float* mod, int shoff, int scoff, int nrows, int lane, int wave, const float* part = nullptr, float* ctx_out = nullptr) {
;     ...
;     for (int m = MLAT + gw; m < nrows; m += NGW) norm_group<1>(m, src_lat, src_ctx, H, gain, mod, shoff, scoff, lane, part, ctx_out);
.LBB0_618:
	s_waitcnt vmcnt(3)
	v_pk_mul_f32 v[42:43], v[16:17], v[16:17]
	v_pk_mul_f32 v[44:45], v[14:15], v[14:15]
	s_waitcnt vmcnt(2)
	v_pk_mul_f32 v[30:31], v[12:13], v[12:13]
	v_pk_mul_f32 v[32:33], v[10:11], v[10:11]
	v_pk_mov_b32 v[46:47], v[44:45], v[42:43] op_sel:[1,0]
	v_mov_b32_e32 v45, v43
	v_pk_add_f32 v[42:43], v[46:47], v[44:45]
	v_pk_mov_b32 v[44:45], v[32:33], v[30:31] op_sel:[1,0]
	v_mov_b32_e32 v33, v31
	s_waitcnt vmcnt(1)
	v_mul_f32_e32 v22, v6, v6
	v_pk_add_f32 v[30:31], v[44:45], v[32:33]
	v_pk_fma_f32 v[32:33], v[6:7], v[6:7], v[22:23] op_sel_hi:[1,1,0]
	v_mul_f32_e32 v22, v8, v8
	v_pk_add_f32 v[42:43], v[42:43], v[42:43] op_sel_hi:[0,1]
	v_pk_add_f32 v[30:31], v[30:31], v[30:31] op_sel_hi:[0,1]
	v_pk_fma_f32 v[44:45], v[8:9], v[8:9], v[22:23] op_sel_hi:[1,1,0]
	s_waitcnt vmcnt(0)
	v_mul_f32_e32 v32, v2, v2
	v_mul_f32_e32 v44, v3, v3
	v_mul_f32_e32 v42, v4, v4
	v_mul_f32_e32 v30, v5, v5
	v_pk_add_f32 v[32:33], v[32:33], v[44:45]
	v_pk_add_f32 v[30:31], v[42:43], v[30:31]
	s_min_i32 s0, s6, 0x8000
	v_pk_add_f32 v[30:31], v[32:33], v[30:31]
	s_ashr_i32 s6, s0, 13
	v_add_f32_e32 v22, v30, v31
	ds_bpermute_b32 v29, v23, v22
	s_waitcnt lgkmcnt(0)
	v_add_f32_e32 v22, v22, v29
	ds_bpermute_b32 v29, v24, v22
	s_waitcnt lgkmcnt(0)
	v_add_f32_e32 v22, v22, v29
	ds_bpermute_b32 v29, v25, v22
	s_waitcnt lgkmcnt(0)
	v_add_f32_e32 v22, v22, v29
	ds_bpermute_b32 v29, v26, v22
	s_waitcnt lgkmcnt(0)
	v_add_f32_e32 v22, v22, v29
	ds_bpermute_b32 v29, v27, v22
	s_waitcnt lgkmcnt(0)
	v_add_f32_e32 v22, v22, v29
	ds_bpermute_b32 v29, v28, v22
	s_waitcnt lgkmcnt(0)
	v_add_f32_e32 v22, v22, v29
	v_fmamk_f32 v22, v22, 0x3a800000, v205
	v_cmp_gt_f32_e32 vcc, s88, v22
	v_mul_f32_e32 v29, 0x4f800000, v22
	s_nop 0
	v_cndmask_b32_e32 v22, v22, v29, vcc
	v_sqrt_f32_e32 v29, v22
	s_nop 0
	v_add_u32_e32 v30, -1, v29
	v_fma_f32 v31, -v30, v29, v22
	v_cmp_ge_f32_e64 s[0:1], 0, v31
	v_add_u32_e32 v31, 1, v29
	s_nop 0
	v_cndmask_b32_e64 v30, v29, v30, s[0:1]
	v_fma_f32 v29, -v31, v29, v22
	v_cmp_lt_f32_e64 s[0:1], 0, v29
	s_nop 1
	v_cndmask_b32_e64 v29, v30, v31, s[0:1]
	v_mul_f32_e32 v30, 0x37800000, v29
	v_cndmask_b32_e32 v29, v29, v30, vcc
	v_cmp_class_f32_e32 vcc, v22, v206
	s_nop 1
	v_cndmask_b32_e32 v22, v29, v22, vcc
	v_div_scale_f32 v29, s[0:1], v22, v22, 1.0
	v_rcp_f32_e32 v30, v29
	s_mul_i32 s0, s6, 0x1800
	s_ashr_i32 s1, s0, 31
	s_lshl_b64 s[0:1], s[0:1], 2
	v_fma_f32 v31, -v29, v30, 1.0
	v_fmac_f32_e32 v30, v31, v30
	v_div_scale_f32 v31, vcc, 1.0, v22, 1.0
	s_add_u32 s0, s72, s0
	v_mul_f32_e32 v32, v31, v30
	s_addc_u32 s1, s74, s1
	v_fma_f32 v33, -v29, v32, v31
	s_add_u32 s6, s0, 0x4000
	v_fmac_f32_e32 v32, v33, v30
	s_addc_u32 s7, s1, 0
	v_fma_f32 v29, -v29, v32, v31
	s_add_u32 s0, s0, 0x3000
	v_div_fmas_f32 v29, v29, v30, v32
	s_addc_u32 s1, s1, 0
	global_load_dwordx4 v[30:33], v[18:19], off nt
	global_load_dwordx4 v[42:45], v34, s[6:7] nt
	global_load_dwordx4 v[46:49], v34, s[0:1] nt
	v_div_fixup_f32 v22, v29, v22, 1.0
	v_pk_mul_f32 v[14:15], v[14:15], v[22:23] op_sel_hi:[1,0]
	v_pk_mul_f32 v[16:17], v[16:17], v[22:23] op_sel_hi:[1,0]
	v_lshlrev_b32_e32 v29, 2, v83
	v_pk_mul_f32 v[10:11], v[10:11], v[22:23] op_sel_hi:[1,0]
	v_pk_mul_f32 v[12:13], v[12:13], v[22:23] op_sel_hi:[1,0]
	v_pk_mul_f32 v[6:7], v[6:7], v[22:23] op_sel_hi:[1,0]
	v_pk_mul_f32 v[8:9], v[8:9], v[22:23] op_sel_hi:[1,0]
	s_add_i32 s78, s78, s52
	v_pk_mul_f32 v[2:3], v[2:3], v[22:23] op_sel_hi:[1,0]
	v_pk_mul_f32 v[4:5], v[4:5], v[22:23] op_sel_hi:[1,0]
	s_waitcnt vmcnt(1)
	v_pk_add_f32 v[42:43], v[42:43], 1.0 op_sel_hi:[1,0]
	v_pk_add_f32 v[44:45], v[44:45], 1.0 op_sel_hi:[1,0]
	v_pk_mul_f32 v[30:31], v[30:31], v[42:43]
	v_pk_mul_f32 v[32:33], v[32:33], v[44:45]
	s_waitcnt vmcnt(0)
	v_pk_fma_f32 v[14:15], v[30:31], v[14:15], v[46:47]
	v_pk_fma_f32 v[16:17], v[32:33], v[16:17], v[48:49]
	v_cvt_pk_bf16_f32 v14, v14, v15
	s_nop 0
	v_cvt_pk_bf16_f32 v15, v16, v17
	global_store_dwordx2 v[20:21], v[14:15], off
	global_load_dwordx4 v[14:17], v[18:19], off offset:1024 nt
	s_nop 0
	global_load_dwordx4 v[30:33], v29, s[6:7] nt
	global_load_dwordx4 v[42:45], v29, s[0:1] nt
	v_lshlrev_b32_e32 v29, 2, v85
	s_waitcnt vmcnt(1)
	v_pk_add_f32 v[30:31], v[30:31], 1.0 op_sel_hi:[1,0]
	v_pk_add_f32 v[32:33], v[32:33], 1.0 op_sel_hi:[1,0]
	v_pk_mul_f32 v[14:15], v[14:15], v[30:31]
	v_pk_mul_f32 v[16:17], v[16:17], v[32:33]
	s_waitcnt vmcnt(0)
	v_pk_fma_f32 v[10:11], v[14:15], v[10:11], v[42:43]
	v_pk_fma_f32 v[12:13], v[16:17], v[12:13], v[44:45]
	v_cvt_pk_bf16_f32 v10, v10, v11
	s_nop 0
	v_cvt_pk_bf16_f32 v11, v12, v13
	global_store_dwordx2 v[20:21], v[10:11], off offset:512
	global_load_dwordx4 v[10:13], v[18:19], off offset:2048 nt
	s_nop 0
	global_load_dwordx4 v[14:17], v29, s[6:7] nt
	global_load_dwordx4 v[30:33], v29, s[0:1] nt
	s_waitcnt vmcnt(1)
	v_pk_add_f32 v[14:15], v[14:15], 1.0 op_sel_hi:[1,0]
	v_pk_add_f32 v[16:17], v[16:17], 1.0 op_sel_hi:[1,0]
	v_pk_mul_f32 v[10:11], v[10:11], v[14:15]
	v_pk_mul_f32 v[12:13], v[12:13], v[16:17]
	s_waitcnt vmcnt(0)
	v_pk_fma_f32 v[6:7], v[6:7], v[10:11], v[30:31]
	v_pk_fma_f32 v[8:9], v[8:9], v[12:13], v[32:33]
	v_cvt_pk_bf16_f32 v6, v6, v7
	v_lshlrev_b32_e32 v14, 2, v87
	v_cvt_pk_bf16_f32 v7, v8, v9
	global_store_dwordx2 v[20:21], v[6:7], off offset:1024
	global_load_dwordx4 v[6:9], v[18:19], off offset:3072 nt
	s_nop 0
	global_load_dwordx4 v[10:13], v14, s[6:7] nt
	s_nop 0
	global_load_dwordx4 v[14:17], v14, s[0:1] nt
	s_add_i32 s0, s78, 0x8000
	s_add_u32 s2, s2, s52
	s_addc_u32 s3, s3, s53
	s_cmp_lt_i32 s0, s14
	s_waitcnt vmcnt(1)
	v_pk_add_f32 v[10:11], v[10:11], 1.0 op_sel_hi:[1,0]
	v_pk_add_f32 v[12:13], v[12:13], 1.0 op_sel_hi:[1,0]
	v_pk_mul_f32 v[6:7], v[6:7], v[10:11]
	v_pk_mul_f32 v[8:9], v[8:9], v[12:13]
	s_waitcnt vmcnt(0)
	v_pk_fma_f32 v[2:3], v[2:3], v[6:7], v[14:15]
	v_pk_fma_f32 v[4:5], v[4:5], v[8:9], v[16:17]
	v_cvt_pk_bf16_f32 v2, v2, v3
	s_nop 0
	v_cvt_pk_bf16_f32 v3, v4, v5
	global_store_dwordx2 v[20:21], v[2:3], off offset:1536
	v_lshl_add_u64 v[20:21], v[20:21], 0, s[66:67]
	s_cbranch_scc0 .LBB0_623
; template <int NR>
; __device__ __forceinline__ void norm_group(int m0, const float* src_lat, const float* src_ctx, bf16* H, const float* gain, const float* mod, int shoff, int scoff, int lane, const float* part, float* ctx_out) {
;     ...
;         for (int j = 0; j < 4; ++j) v[i][j] = *((const f32x4*)(xr + (size_t)i * D) + lane + 64 * j);
;     if (part && m0 >= MLAT) {
; #pragma unroll
;         for (int i = 0; i < NR; ++i)
; #pragma unroll
;             for (int j = 0; j < 4; ++j) { const size_t o = (size_t)(m0 - MLAT + i) * D + 4 * (lane + 64 * j);
;                 const f32x4 p0 = *(const f32x4*)(part + o), p1 = *(const f32x4*)(part + (size_t)MCTX * D + o), p2 = *(const f32x4*)(part + (size_t)2 * MCTX * D + o), p3 = *(const f32x4*)(part + (size_t)3 * MCTX * D + o);
;                 v[i][j] = v[i][j] + ((p0 + p1) + (p2 + p3)); *(f32x4*)(ctx_out + o) = v[i][j]; }
.LBB0_619:
	s_add_i32 s6, s78, 0x8000
	s_cmp_lt_i32 s6, 0x8000
	s_cselect_b32 s1, s3, 0
	s_cselect_b32 s0, s2, s78
	s_cselect_b32 s7, s5, s95
	s_cselect_b32 s15, s4, s94
	s_lshl_b64 s[0:1], s[0:1], 12
	s_add_u32 s0, s15, s0
	s_addc_u32 s1, s7, s1
	global_load_dwordx4 v[14:17], v36, s[0:1] nt
	global_load_dwordx4 v[10:13], v36, s[0:1] offset:1024 nt
	global_load_dwordx4 v[6:9], v36, s[0:1] offset:2048 nt
	global_load_dwordx4 v[2:5], v36, s[0:1] offset:3072 nt
	s_cmpk_gt_i32 s6, 0x7fff
	s_cselect_b64 s[0:1], -1, 0
	s_and_b64 s[16:17], s[46:47], s[0:1]
	s_mov_b64 s[0:1], -1
	s_and_b64 vcc, exec, s[16:17]
	s_cbranch_vccnz .LBB0_621
	s_mov_b64 s[0:1], 0
.LBB0_621:
	s_andn2_b64 vcc, exec, s[0:1]
	s_cbranch_vccnz .LBB0_618
	s_lshl_b64 s[0:1], s[78:79], 10
	v_mov_b32_e32 v31, s1
	v_or_b32_e32 v30, s0, v81
	v_lshlrev_b64 v[54:55], 2, v[30:31]
	v_lshl_add_u64 v[30:31], s[50:51], 0, v[54:55]
	v_lshl_add_u64 v[42:43], s[8:9], 0, v[54:55]
	v_lshl_add_u64 v[46:47], s[10:11], 0, v[54:55]
	v_lshl_add_u64 v[50:51], s[12:13], 0, v[54:55]
	global_load_dwordx4 v[30:33], v[30:31], off nt
	s_nop 0
	global_load_dwordx4 v[42:45], v[42:43], off nt
	s_nop 0
	global_load_dwordx4 v[46:49], v[46:47], off nt
	s_waitcnt vmcnt(1)
	v_pk_add_f32 v[32:33], v[32:33], v[44:45]
	global_load_dwordx4 v[50:53], v[50:51], off nt
	v_pk_add_f32 v[30:31], v[30:31], v[42:43]
	s_waitcnt vmcnt(0)
	v_pk_add_f32 v[42:43], v[48:49], v[52:53]
	v_pk_add_f32 v[44:45], v[46:47], v[50:51]
	v_pk_add_f32 v[32:33], v[32:33], v[42:43]
	v_pk_add_f32 v[30:31], v[30:31], v[44:45]
	v_pk_add_f32 v[16:17], v[16:17], v[32:33]
	v_pk_add_f32 v[14:15], v[14:15], v[30:31]
	v_lshl_add_u64 v[30:31], s[94:95], 0, v[54:55]
	global_store_dwordx4 v[30:31], v[14:17], off
	v_mov_b32_e32 v31, s1
	v_or_b32_e32 v30, s0, v83
	v_lshlrev_b64 v[54:55], 2, v[30:31]
	v_lshl_add_u64 v[30:31], s[50:51], 0, v[54:55]
	v_lshl_add_u64 v[42:43], s[8:9], 0, v[54:55]
	v_lshl_add_u64 v[46:47], s[10:11], 0, v[54:55]
	v_lshl_add_u64 v[50:51], s[12:13], 0, v[54:55]
	global_load_dwordx4 v[30:33], v[30:31], off nt
	s_nop 0
	global_load_dwordx4 v[42:45], v[42:43], off nt
	s_nop 0
	global_load_dwordx4 v[46:49], v[46:47], off nt
	s_waitcnt vmcnt(1)
	v_pk_add_f32 v[32:33], v[32:33], v[44:45]
	global_load_dwordx4 v[50:53], v[50:51], off nt
	v_pk_add_f32 v[30:31], v[30:31], v[42:43]
	s_waitcnt vmcnt(0)
	v_pk_add_f32 v[42:43], v[48:49], v[52:53]
	v_pk_add_f32 v[44:45], v[46:47], v[50:51]
	v_pk_add_f32 v[32:33], v[32:33], v[42:43]
	v_pk_add_f32 v[30:31], v[30:31], v[44:45]
	v_pk_add_f32 v[12:13], v[12:13], v[32:33]
	v_pk_add_f32 v[10:11], v[10:11], v[30:31]
	v_lshl_add_u64 v[30:31], s[94:95], 0, v[54:55]
	global_store_dwordx4 v[30:31], v[10:13], off
	v_mov_b32_e32 v31, s1
	v_or_b32_e32 v30, s0, v85
	v_lshlrev_b64 v[54:55], 2, v[30:31]
	v_lshl_add_u64 v[30:31], s[50:51], 0, v[54:55]
	v_lshl_add_u64 v[42:43], s[8:9], 0, v[54:55]
	v_lshl_add_u64 v[46:47], s[10:11], 0, v[54:55]
	v_lshl_add_u64 v[50:51], s[12:13], 0, v[54:55]
	global_load_dwordx4 v[30:33], v[30:31], off nt
	s_nop 0
	global_load_dwordx4 v[42:45], v[42:43], off nt
	s_nop 0
	global_load_dwordx4 v[46:49], v[46:47], off nt
	s_waitcnt vmcnt(1)
	v_pk_add_f32 v[32:33], v[32:33], v[44:45]
	global_load_dwordx4 v[50:53], v[50:51], off nt
	v_pk_add_f32 v[30:31], v[30:31], v[42:43]
	s_waitcnt vmcnt(0)
	v_pk_add_f32 v[42:43], v[48:49], v[52:53]
	v_pk_add_f32 v[44:45], v[46:47], v[50:51]
	v_pk_add_f32 v[32:33], v[32:33], v[42:43]
	v_pk_add_f32 v[30:31], v[30:31], v[44:45]
	v_pk_add_f32 v[8:9], v[8:9], v[32:33]
	v_pk_add_f32 v[6:7], v[6:7], v[30:31]
	v_lshl_add_u64 v[30:31], s[94:95], 0, v[54:55]
	global_store_dwordx4 v[30:31], v[6:9], off
	v_mov_b32_e32 v31, s1
	v_or_b32_e32 v30, s0, v87
	v_lshlrev_b64 v[54:55], 2, v[30:31]
	v_lshl_add_u64 v[30:31], s[50:51], 0, v[54:55]
	v_lshl_add_u64 v[42:43], s[8:9], 0, v[54:55]
	v_lshl_add_u64 v[46:47], s[10:11], 0, v[54:55]
	v_lshl_add_u64 v[50:51], s[12:13], 0, v[54:55]
	global_load_dwordx4 v[30:33], v[30:31], off nt
	s_nop 0
	global_load_dwordx4 v[42:45], v[42:43], off nt
	s_nop 0
	global_load_dwordx4 v[46:49], v[46:47], off nt
	s_waitcnt vmcnt(1)
	v_pk_add_f32 v[32:33], v[32:33], v[44:45]
	global_load_dwordx4 v[50:53], v[50:51], off nt
	v_pk_add_f32 v[30:31], v[30:31], v[42:43]
	s_waitcnt vmcnt(0)
	v_pk_add_f32 v[42:43], v[48:49], v[52:53]
	v_pk_add_f32 v[44:45], v[46:47], v[50:51]
	v_pk_add_f32 v[32:33], v[32:33], v[42:43]
	v_pk_add_f32 v[30:31], v[30:31], v[44:45]
	v_pk_add_f32 v[4:5], v[4:5], v[32:33]
	v_pk_add_f32 v[2:3], v[2:3], v[30:31]
	v_lshl_add_u64 v[30:31], s[94:95], 0, v[54:55]
	global_store_dwordx4 v[30:31], v[2:5], off
	s_branch .LBB0_618
